# baseline (speedup 1.0000x reference)
.LBB0_377:
	s_add_u32 s3, s16, 0xfff80080
	s_addc_u32 s18, s17, -1
	s_add_i32 s42, 0, 0x10000
	s_cmp_eq_u32 s41, 28
	s_cselect_b32 s21, s11, s18
	s_cselect_b32 s20, s31, s3
	v_add_u32_e32 v152, s42, v155
	s_cselect_b32 s19, s9, s40
	s_cselect_b32 s18, s34, s35
	s_add_i32 s3, 0, 0x14000
	ds_read_b128 v[140:143], v152
	ds_read_b128 v[144:147], v152 offset:1024
	ds_read_b128 v[148:151], v152 offset:2048
	ds_read_b128 v[158:161], v152 offset:3072
	v_add_u32_e32 v152, s3, v155
	ds_read_b128 v[162:165], v152
	ds_read_b128 v[166:169], v152 offset:1024
	ds_read_b128 v[170:173], v152 offset:2048
	ds_read_b128 v[174:177], v152 offset:3072
	v_lshl_add_u64 v[152:153], s[16:17], 0, v[136:137]
	s_add_i32 m0, s22, 0xc000
	ds_read_b128 v[188:191], v157
	ds_read_b128 v[192:195], v157 offset:1024
	ds_read_b128 v[196:199], v157 offset:2048
	ds_read_b128 v[200:203], v157 offset:3072
	ds_read_b128 v[204:207], v157 offset:4096
	ds_read_b128 v[218:221], v157 offset:5120
	ds_read_b128 v[222:225], v157 offset:6144
	ds_read_b128 v[226:229], v157 offset:7168
	global_load_lds_dwordx4 v[152:153], off
	v_lshl_add_u64 v[152:153], s[16:17], 0, v[138:139]
	s_add_i32 m0, s22, 0xe000
	s_nop 0
	global_load_lds_dwordx4 v[152:153], off
	s_waitcnt vmcnt(8)
	s_waitcnt lgkmcnt(0)
	s_waitcnt lgkmcnt(0)
	v_mfma_f32_16x16x32_bf16 v[126:129], v[140:143], v[188:191], v[126:129]
	v_mfma_f32_16x16x32_bf16 v[122:125], v[148:151], v[188:191], v[122:125]
	v_mfma_f32_16x16x32_bf16 v[110:113], v[140:143], v[196:199], v[110:113]
	v_mfma_f32_16x16x32_bf16 v[106:109], v[148:151], v[196:199], v[106:109]
	s_barrier
	s_setprio 1
	v_mfma_f32_16x16x32_bf16 v[94:97], v[140:143], v[204:207], v[94:97]
	v_mfma_f32_16x16x32_bf16 v[90:93], v[148:151], v[204:207], v[90:93]
	v_mfma_f32_16x16x32_bf16 v[78:81], v[140:143], v[222:225], v[78:81]
	v_mfma_f32_16x16x32_bf16 v[74:77], v[148:151], v[222:225], v[74:77]
	v_mfma_f32_16x16x32_bf16 v[126:129], v[144:147], v[192:195], v[126:129]
	v_mfma_f32_16x16x32_bf16 v[122:125], v[158:161], v[192:195], v[122:125]
	v_mfma_f32_16x16x32_bf16 v[110:113], v[144:147], v[200:203], v[110:113]
	v_mfma_f32_16x16x32_bf16 v[106:109], v[158:161], v[200:203], v[106:109]
	v_mfma_f32_16x16x32_bf16 v[94:97], v[144:147], v[218:221], v[94:97]
	v_mfma_f32_16x16x32_bf16 v[90:93], v[158:161], v[218:221], v[90:93]
	v_mfma_f32_16x16x32_bf16 v[78:81], v[144:147], v[226:229], v[78:81]
	v_mfma_f32_16x16x32_bf16 v[74:77], v[158:161], v[226:229], v[74:77]
	s_setprio 0
	s_setprio 1
	v_mfma_f32_16x16x32_bf16 v[118:121], v[162:165], v[188:191], v[118:121]
	v_mfma_f32_16x16x32_bf16 v[114:117], v[170:173], v[188:191], v[114:117]
	v_mfma_f32_16x16x32_bf16 v[102:105], v[162:165], v[196:199], v[102:105]
	v_mfma_f32_16x16x32_bf16 v[98:101], v[170:173], v[196:199], v[98:101]
	v_mfma_f32_16x16x32_bf16 v[86:89], v[162:165], v[204:207], v[86:89]
	v_mfma_f32_16x16x32_bf16 v[82:85], v[170:173], v[204:207], v[82:85]
	v_mfma_f32_16x16x32_bf16 v[70:73], v[162:165], v[222:225], v[70:73]
	v_mfma_f32_16x16x32_bf16 v[66:69], v[170:173], v[222:225], v[66:69]
	v_mfma_f32_16x16x32_bf16 v[118:121], v[166:169], v[192:195], v[118:121]
	v_mfma_f32_16x16x32_bf16 v[114:117], v[174:177], v[192:195], v[114:117]
	v_mfma_f32_16x16x32_bf16 v[102:105], v[166:169], v[200:203], v[102:105]
	v_mfma_f32_16x16x32_bf16 v[98:101], v[174:177], v[200:203], v[98:101]
	v_mfma_f32_16x16x32_bf16 v[86:89], v[166:169], v[218:221], v[86:89]
	v_mfma_f32_16x16x32_bf16 v[82:85], v[174:177], v[218:221], v[82:85]
	v_mfma_f32_16x16x32_bf16 v[70:73], v[166:169], v[226:229], v[70:73]
	v_mfma_f32_16x16x32_bf16 v[66:69], v[174:177], v[226:229], v[66:69]
	s_setprio 0
	s_barrier
	s_add_i32 s42, s42, s2
	v_lshl_add_u64 v[152:153], s[18:19], 0, v[0:1]
	s_mov_b32 m0, s42
	ds_read_b128 v[188:191], v157 offset:16384
	ds_read_b128 v[192:195], v157 offset:17408
	ds_read_b128 v[196:199], v157 offset:18432
	ds_read_b128 v[200:203], v157 offset:19456
	ds_read_b128 v[204:207], v157 offset:20480
	ds_read_b128 v[218:221], v157 offset:21504
	ds_read_b128 v[222:225], v157 offset:22528
	ds_read_b128 v[226:229], v157 offset:23552
	global_load_lds_dwordx4 v[152:153], off
	s_add_i32 m0, s42, 0x2000
	s_add_u32 s44, s18, 0x80000
	v_lshl_add_u64 v[178:179], s[18:19], 0, v[130:131]
	s_addc_u32 s45, s19, 0
	s_add_i32 s3, s3, s2
	global_load_lds_dwordx4 v[178:179], off
	v_lshl_add_u64 v[180:181], s[44:45], 0, v[0:1]
	s_mov_b32 m0, s3
	v_lshl_add_u64 v[182:183], s[20:21], 0, v[132:133]
	global_load_lds_dwordx4 v[180:181], off
	v_lshl_add_u64 v[180:181], s[44:45], 0, v[130:131]
	s_add_i32 m0, s3, 0x2000
	s_nop 0
	global_load_lds_dwordx4 v[180:181], off
	v_lshl_add_u64 v[180:181], s[20:21], 0, v[134:135]
	s_mov_b32 m0, s22
	s_nop 0
	global_load_lds_dwordx4 v[180:181], off
	s_mov_b32 m0, s23
	s_nop 0
	global_load_lds_dwordx4 v[182:183], off
	s_waitcnt vmcnt(8)
	s_waitcnt lgkmcnt(0)
	s_waitcnt lgkmcnt(0)
	v_mfma_f32_16x16x32_bf16 v[62:65], v[140:143], v[188:191], v[62:65]
	v_mfma_f32_16x16x32_bf16 v[58:61], v[148:151], v[188:191], v[58:61]
	v_mfma_f32_16x16x32_bf16 v[46:49], v[140:143], v[196:199], v[46:49]
	v_mfma_f32_16x16x32_bf16 v[42:45], v[148:151], v[196:199], v[42:45]
	s_barrier
	s_setprio 1
	v_mfma_f32_16x16x32_bf16 v[30:33], v[140:143], v[204:207], v[30:33]
	v_mfma_f32_16x16x32_bf16 v[26:29], v[148:151], v[204:207], v[26:29]
	v_mfma_f32_16x16x32_bf16 v[14:17], v[140:143], v[222:225], v[14:17]
	v_mfma_f32_16x16x32_bf16 v[6:9], v[148:151], v[222:225], v[6:9]
	v_mfma_f32_16x16x32_bf16 v[62:65], v[144:147], v[192:195], v[62:65]
	v_mfma_f32_16x16x32_bf16 v[58:61], v[158:161], v[192:195], v[58:61]
	v_mfma_f32_16x16x32_bf16 v[46:49], v[144:147], v[200:203], v[46:49]
	v_mfma_f32_16x16x32_bf16 v[42:45], v[158:161], v[200:203], v[42:45]
	v_mfma_f32_16x16x32_bf16 v[30:33], v[144:147], v[218:221], v[30:33]
	v_mfma_f32_16x16x32_bf16 v[26:29], v[158:161], v[218:221], v[26:29]
	v_mfma_f32_16x16x32_bf16 v[14:17], v[144:147], v[226:229], v[14:17]
	v_mfma_f32_16x16x32_bf16 v[6:9], v[158:161], v[226:229], v[6:9]
	s_setprio 0
	s_setprio 1
	v_mfma_f32_16x16x32_bf16 v[54:57], v[162:165], v[188:191], v[54:57]
	v_mfma_f32_16x16x32_bf16 v[50:53], v[170:173], v[188:191], v[50:53]
	v_mfma_f32_16x16x32_bf16 v[38:41], v[162:165], v[196:199], v[38:41]
	v_mfma_f32_16x16x32_bf16 v[34:37], v[170:173], v[196:199], v[34:37]
	v_mfma_f32_16x16x32_bf16 v[22:25], v[162:165], v[204:207], v[22:25]
	v_mfma_f32_16x16x32_bf16 v[18:21], v[170:173], v[204:207], v[18:21]
	v_mfma_f32_16x16x32_bf16 v[10:13], v[162:165], v[222:225], v[10:13]
	v_mfma_f32_16x16x32_bf16 v[2:5], v[170:173], v[222:225], v[2:5]
	v_mfma_f32_16x16x32_bf16 v[54:57], v[166:169], v[192:195], v[54:57]
	v_mfma_f32_16x16x32_bf16 v[50:53], v[174:177], v[192:195], v[50:53]
	v_mfma_f32_16x16x32_bf16 v[38:41], v[166:169], v[200:203], v[38:41]
	v_mfma_f32_16x16x32_bf16 v[34:37], v[174:177], v[200:203], v[34:37]
	v_mfma_f32_16x16x32_bf16 v[22:25], v[166:169], v[218:221], v[22:25]
	v_mfma_f32_16x16x32_bf16 v[18:21], v[174:177], v[218:221], v[18:21]
	v_mfma_f32_16x16x32_bf16 v[10:13], v[166:169], v[226:229], v[10:13]
	v_mfma_f32_16x16x32_bf16 v[2:5], v[174:177], v[226:229], v[2:5]
	s_setprio 0
	s_barrier
	s_add_i32 s3, 0, 0x18000
	s_add_i32 s42, 0, 0x1c000
	v_add_u32_e32 v158, s3, v155
	v_add_u32_e32 v174, s42, v155
	ds_read_b128 v[140:143], v158
	ds_read_b128 v[144:147], v158 offset:1024
	ds_read_b128 v[148:151], v158 offset:2048
	ds_read_b128 v[158:161], v158 offset:3072
	ds_read_b128 v[162:165], v174
	ds_read_b128 v[166:169], v174 offset:1024
	ds_read_b128 v[170:173], v174 offset:2048
	ds_read_b128 v[174:177], v174 offset:3072
	s_add_u32 s20, s20, 0x80000
	s_addc_u32 s21, s21, 0
	s_mov_b32 m0, s24
	v_lshl_add_u64 v[184:185], s[20:21], 0, v[134:135]
	ds_read_b128 v[188:191], v157 offset:32768
	ds_read_b128 v[192:195], v157 offset:33792
	ds_read_b128 v[196:199], v157 offset:34816
	ds_read_b128 v[200:203], v157 offset:35840
	ds_read_b128 v[204:207], v157 offset:36864
	ds_read_b128 v[218:221], v157 offset:37888
	ds_read_b128 v[222:225], v157 offset:38912
	ds_read_b128 v[226:229], v157 offset:39936
	global_load_lds_dwordx4 v[184:185], off
	v_lshl_add_u64 v[184:185], s[20:21], 0, v[132:133]
	s_mov_b32 m0, s25
	s_nop 0
	global_load_lds_dwordx4 v[184:185], off
	s_waitcnt vmcnt(8)
	s_waitcnt lgkmcnt(0)
	s_waitcnt lgkmcnt(0)
	v_mfma_f32_16x16x32_bf16 v[126:129], v[140:143], v[188:191], v[126:129]
	v_mfma_f32_16x16x32_bf16 v[122:125], v[148:151], v[188:191], v[122:125]
	v_mfma_f32_16x16x32_bf16 v[110:113], v[140:143], v[196:199], v[110:113]
	v_mfma_f32_16x16x32_bf16 v[106:109], v[148:151], v[196:199], v[106:109]
	s_barrier
	s_setprio 1
	v_mfma_f32_16x16x32_bf16 v[94:97], v[140:143], v[204:207], v[94:97]
	v_mfma_f32_16x16x32_bf16 v[90:93], v[148:151], v[204:207], v[90:93]
	v_mfma_f32_16x16x32_bf16 v[78:81], v[140:143], v[222:225], v[78:81]
	v_mfma_f32_16x16x32_bf16 v[74:77], v[148:151], v[222:225], v[74:77]
	v_mfma_f32_16x16x32_bf16 v[126:129], v[144:147], v[192:195], v[126:129]
	v_mfma_f32_16x16x32_bf16 v[122:125], v[158:161], v[192:195], v[122:125]
	v_mfma_f32_16x16x32_bf16 v[110:113], v[144:147], v[200:203], v[110:113]
	v_mfma_f32_16x16x32_bf16 v[106:109], v[158:161], v[200:203], v[106:109]
	v_mfma_f32_16x16x32_bf16 v[94:97], v[144:147], v[218:221], v[94:97]
	v_mfma_f32_16x16x32_bf16 v[90:93], v[158:161], v[218:221], v[90:93]
	v_mfma_f32_16x16x32_bf16 v[78:81], v[144:147], v[226:229], v[78:81]
	v_mfma_f32_16x16x32_bf16 v[74:77], v[158:161], v[226:229], v[74:77]
	s_setprio 0
	s_setprio 1
	v_mfma_f32_16x16x32_bf16 v[118:121], v[162:165], v[188:191], v[118:121]
	v_mfma_f32_16x16x32_bf16 v[114:117], v[170:173], v[188:191], v[114:117]
	v_mfma_f32_16x16x32_bf16 v[102:105], v[162:165], v[196:199], v[102:105]
	v_mfma_f32_16x16x32_bf16 v[98:101], v[170:173], v[196:199], v[98:101]
	v_mfma_f32_16x16x32_bf16 v[86:89], v[162:165], v[204:207], v[86:89]
	v_mfma_f32_16x16x32_bf16 v[82:85], v[170:173], v[204:207], v[82:85]
	v_mfma_f32_16x16x32_bf16 v[70:73], v[162:165], v[222:225], v[70:73]
	v_mfma_f32_16x16x32_bf16 v[66:69], v[170:173], v[222:225], v[66:69]
	v_mfma_f32_16x16x32_bf16 v[118:121], v[166:169], v[192:195], v[118:121]
	v_mfma_f32_16x16x32_bf16 v[114:117], v[174:177], v[192:195], v[114:117]
	v_mfma_f32_16x16x32_bf16 v[102:105], v[166:169], v[200:203], v[102:105]
	v_mfma_f32_16x16x32_bf16 v[98:101], v[174:177], v[200:203], v[98:101]
	v_mfma_f32_16x16x32_bf16 v[86:89], v[166:169], v[218:221], v[86:89]
	v_mfma_f32_16x16x32_bf16 v[82:85], v[174:177], v[218:221], v[82:85]
	v_mfma_f32_16x16x32_bf16 v[70:73], v[166:169], v[226:229], v[70:73]
	v_mfma_f32_16x16x32_bf16 v[66:69], v[174:177], v[226:229], v[66:69]
	s_setprio 0
	s_barrier
	s_add_i32 s3, s3, s2
	v_lshl_add_u64 v[152:153], v[152:153], 0, s[52:53]
	s_mov_b32 m0, s3
	ds_read_b128 v[188:191], v157 offset:49152
	ds_read_b128 v[192:195], v157 offset:50176
	ds_read_b128 v[196:199], v157 offset:51200
	ds_read_b128 v[200:203], v157 offset:52224
	ds_read_b128 v[204:207], v157 offset:53248
	ds_read_b128 v[218:221], v157 offset:54272
	ds_read_b128 v[222:225], v157 offset:55296
	ds_read_b128 v[226:229], v157 offset:56320
	global_load_lds_dwordx4 v[152:153], off
	s_add_i32 m0, s3, 0x2000
	s_add_u32 s18, s18, 0x80080
	v_lshl_add_u64 v[152:153], v[178:179], 0, s[52:53]
	s_addc_u32 s19, s19, 0
	s_add_i32 s3, s42, s2
	global_load_lds_dwordx4 v[152:153], off
	v_lshl_add_u64 v[152:153], s[18:19], 0, v[0:1]
	s_mov_b32 m0, s3
	s_nop 0
	global_load_lds_dwordx4 v[152:153], off
	v_lshl_add_u64 v[152:153], s[18:19], 0, v[130:131]
	s_add_i32 m0, s3, 0x2000
	s_nop 0
	global_load_lds_dwordx4 v[152:153], off
	v_lshl_add_u64 v[152:153], v[180:181], 0, s[52:53]
	s_mov_b32 m0, s26
	s_nop 0
	global_load_lds_dwordx4 v[152:153], off
	v_lshl_add_u64 v[152:153], v[182:183], 0, s[52:53]
	s_mov_b32 m0, s27
	s_nop 0
	global_load_lds_dwordx4 v[152:153], off
	s_waitcnt vmcnt(8)
	s_waitcnt lgkmcnt(0)
	s_waitcnt lgkmcnt(0)
	v_mfma_f32_16x16x32_bf16 v[62:65], v[140:143], v[188:191], v[62:65]
	v_mfma_f32_16x16x32_bf16 v[58:61], v[148:151], v[188:191], v[58:61]
	v_mfma_f32_16x16x32_bf16 v[46:49], v[140:143], v[196:199], v[46:49]
	v_mfma_f32_16x16x32_bf16 v[42:45], v[148:151], v[196:199], v[42:45]
	s_barrier
	s_setprio 1
	v_mfma_f32_16x16x32_bf16 v[30:33], v[140:143], v[204:207], v[30:33]
	v_mfma_f32_16x16x32_bf16 v[26:29], v[148:151], v[204:207], v[26:29]
	v_mfma_f32_16x16x32_bf16 v[14:17], v[140:143], v[222:225], v[14:17]
	v_mfma_f32_16x16x32_bf16 v[6:9], v[148:151], v[222:225], v[6:9]
	v_mfma_f32_16x16x32_bf16 v[62:65], v[144:147], v[192:195], v[62:65]
	v_mfma_f32_16x16x32_bf16 v[58:61], v[158:161], v[192:195], v[58:61]
	v_mfma_f32_16x16x32_bf16 v[46:49], v[144:147], v[200:203], v[46:49]
	v_mfma_f32_16x16x32_bf16 v[42:45], v[158:161], v[200:203], v[42:45]
	v_mfma_f32_16x16x32_bf16 v[30:33], v[144:147], v[218:221], v[30:33]
	v_mfma_f32_16x16x32_bf16 v[26:29], v[158:161], v[218:221], v[26:29]
	v_mfma_f32_16x16x32_bf16 v[14:17], v[144:147], v[226:229], v[14:17]
	v_mfma_f32_16x16x32_bf16 v[6:9], v[158:161], v[226:229], v[6:9]
	s_setprio 0
	s_setprio 1
	v_mfma_f32_16x16x32_bf16 v[54:57], v[162:165], v[188:191], v[54:57]
	v_mfma_f32_16x16x32_bf16 v[50:53], v[170:173], v[188:191], v[50:53]
	v_mfma_f32_16x16x32_bf16 v[38:41], v[162:165], v[196:199], v[38:41]
	v_mfma_f32_16x16x32_bf16 v[34:37], v[170:173], v[196:199], v[34:37]
	v_mfma_f32_16x16x32_bf16 v[22:25], v[162:165], v[204:207], v[22:25]
	v_mfma_f32_16x16x32_bf16 v[18:21], v[170:173], v[204:207], v[18:21]
	v_mfma_f32_16x16x32_bf16 v[10:13], v[162:165], v[222:225], v[10:13]
	v_mfma_f32_16x16x32_bf16 v[2:5], v[170:173], v[222:225], v[2:5]
	v_mfma_f32_16x16x32_bf16 v[54:57], v[166:169], v[192:195], v[54:57]
	v_mfma_f32_16x16x32_bf16 v[50:53], v[174:177], v[192:195], v[50:53]
	v_mfma_f32_16x16x32_bf16 v[38:41], v[166:169], v[200:203], v[38:41]
	v_mfma_f32_16x16x32_bf16 v[34:37], v[174:177], v[200:203], v[34:37]
	v_mfma_f32_16x16x32_bf16 v[22:25], v[166:169], v[218:221], v[22:25]
	v_mfma_f32_16x16x32_bf16 v[18:21], v[174:177], v[218:221], v[18:21]
	v_mfma_f32_16x16x32_bf16 v[10:13], v[166:169], v[226:229], v[10:13]
	v_mfma_f32_16x16x32_bf16 v[2:5], v[174:177], v[226:229], v[2:5]
	s_setprio 0
	s_barrier
	s_add_i32 s41, s41, 2
	s_add_u32 s16, s16, 0x100
	s_addc_u32 s17, s17, 0
	s_add_u32 s35, s35, 0x100
	s_addc_u32 s40, s40, 0
	s_cmp_gt_u32 s41, 29
	s_cbranch_scc0 .LBB0_377
	s_and_b64 vcc, exec, s[6:7]
	s_movk_i32 s40, 0x4000
	s_movk_i32 s41, 0x6000
	s_cbranch_vccz .LBB0_380
	s_barrier

.LBB0_399:
	s_add_u32 s3, s0, 0xfff80080
	s_addc_u32 s4, s1, -1
	s_add_i32 s42, 0, 0x10000
	s_cmp_eq_u32 s46, 28
	s_cselect_b32 s7, s8, s4
	s_cselect_b32 s6, s9, s3
	v_add_u32_e32 v0, s42, v206
	s_cselect_b32 s5, s19, s27
	s_cselect_b32 s4, s21, s26
	s_add_i32 s3, 0, 0x14000
	ds_read_b128 v[130:133], v0
	ds_read_b128 v[134:137], v0 offset:1024
	ds_read_b128 v[138:141], v0 offset:2048
	ds_read_b128 v[142:145], v0 offset:3072
	v_add_u32_e32 v0, s3, v206
	ds_read_b128 v[146:149], v0
	ds_read_b128 v[150:153], v0 offset:1024
	s_waitcnt lgkmcnt(0)
	ds_read_b128 v[154:157], v0 offset:2048
	ds_read_b128 v[158:161], v0 offset:3072
	v_lshl_add_u64 v[176:177], s[0:1], 0, v[170:171]
	s_add_i32 m0, s28, 0xc000
	ds_read_b128 v[196:199], v218
	ds_read_b128 v[200:203], v218 offset:1024
	ds_read_b128 v[220:223], v218 offset:2048
	ds_read_b128 v[224:227], v218 offset:3072
	ds_read_b128 v[228:231], v218 offset:4096
	ds_read_b128 v[232:235], v218 offset:5120
	ds_read_b128 v[236:239], v218 offset:6144
	ds_read_b128 v[240:243], v218 offset:7168
	global_load_lds_dwordx4 v[176:177], off
	v_lshl_add_u64 v[176:177], s[0:1], 0, v[172:173]
	s_add_i32 m0, s28, 0xe000
	s_nop 0
	global_load_lds_dwordx4 v[176:177], off
	s_waitcnt vmcnt(8)
	s_waitcnt lgkmcnt(0)
	s_waitcnt lgkmcnt(0)
	v_mfma_f32_16x16x32_bf16 v[126:129], v[130:133], v[196:199], v[126:129]
	v_mfma_f32_16x16x32_bf16 v[122:125], v[138:141], v[196:199], v[122:125]
	v_mfma_f32_16x16x32_bf16 v[118:121], v[130:133], v[220:223], v[118:121]
	v_mfma_f32_16x16x32_bf16 v[114:117], v[138:141], v[220:223], v[114:117]
	s_barrier
	s_setprio 1
	v_mfma_f32_16x16x32_bf16 v[110:113], v[130:133], v[228:231], v[110:113]
	v_mfma_f32_16x16x32_bf16 v[106:109], v[138:141], v[228:231], v[106:109]
	v_mfma_f32_16x16x32_bf16 v[102:105], v[130:133], v[236:239], v[102:105]
	v_mfma_f32_16x16x32_bf16 v[98:101], v[138:141], v[236:239], v[98:101]
	v_mfma_f32_16x16x32_bf16 v[126:129], v[134:137], v[200:203], v[126:129]
	v_mfma_f32_16x16x32_bf16 v[122:125], v[142:145], v[200:203], v[122:125]
	v_mfma_f32_16x16x32_bf16 v[118:121], v[134:137], v[224:227], v[118:121]
	v_mfma_f32_16x16x32_bf16 v[114:117], v[142:145], v[224:227], v[114:117]
	v_mfma_f32_16x16x32_bf16 v[110:113], v[134:137], v[232:235], v[110:113]
	v_mfma_f32_16x16x32_bf16 v[106:109], v[142:145], v[232:235], v[106:109]
	v_mfma_f32_16x16x32_bf16 v[102:105], v[134:137], v[240:243], v[102:105]
	v_mfma_f32_16x16x32_bf16 v[98:101], v[142:145], v[240:243], v[98:101]
	s_setprio 0
	s_setprio 1
	v_mfma_f32_16x16x32_bf16 v[94:97], v[146:149], v[196:199], v[94:97]
	v_mfma_f32_16x16x32_bf16 v[90:93], v[154:157], v[196:199], v[90:93]
	v_mfma_f32_16x16x32_bf16 v[86:89], v[146:149], v[220:223], v[86:89]
	v_mfma_f32_16x16x32_bf16 v[82:85], v[154:157], v[220:223], v[82:85]
	v_mfma_f32_16x16x32_bf16 v[78:81], v[146:149], v[228:231], v[78:81]
	v_mfma_f32_16x16x32_bf16 v[74:77], v[154:157], v[228:231], v[74:77]
	v_mfma_f32_16x16x32_bf16 v[70:73], v[146:149], v[236:239], v[70:73]
	v_mfma_f32_16x16x32_bf16 v[66:69], v[154:157], v[236:239], v[66:69]
	v_mfma_f32_16x16x32_bf16 v[94:97], v[150:153], v[200:203], v[94:97]
	v_mfma_f32_16x16x32_bf16 v[90:93], v[158:161], v[200:203], v[90:93]
	v_mfma_f32_16x16x32_bf16 v[86:89], v[150:153], v[224:227], v[86:89]
	v_mfma_f32_16x16x32_bf16 v[82:85], v[158:161], v[224:227], v[82:85]
	v_mfma_f32_16x16x32_bf16 v[78:81], v[150:153], v[232:235], v[78:81]
	v_mfma_f32_16x16x32_bf16 v[74:77], v[158:161], v[232:235], v[74:77]
	v_mfma_f32_16x16x32_bf16 v[70:73], v[150:153], v[240:243], v[70:73]
	v_mfma_f32_16x16x32_bf16 v[66:69], v[158:161], v[240:243], v[66:69]
	s_setprio 0
	s_barrier
	s_add_i32 s42, s42, s2
	v_lshl_add_u64 v[176:177], s[4:5], 0, v[166:167]
	s_mov_b32 m0, s42
	ds_read_b128 v[196:199], v218 offset:16384
	ds_read_b128 v[200:203], v218 offset:17408
	ds_read_b128 v[220:223], v218 offset:18432
	ds_read_b128 v[224:227], v218 offset:19456
	ds_read_b128 v[228:231], v218 offset:20480
	ds_read_b128 v[232:235], v218 offset:21504
	ds_read_b128 v[236:239], v218 offset:22528
	ds_read_b128 v[240:243], v218 offset:23552
	global_load_lds_dwordx4 v[176:177], off
	s_add_i32 m0, s42, 0x2000
	s_add_u32 s56, s4, 0x80000
	v_lshl_add_u64 v[178:179], s[4:5], 0, v[162:163]
	s_addc_u32 s57, s5, 0
	s_add_i32 s3, s3, s2
	global_load_lds_dwordx4 v[178:179], off
	v_lshl_add_u64 v[244:245], s[56:57], 0, v[166:167]
	s_mov_b32 m0, s3
	v_lshl_add_u64 v[246:247], s[6:7], 0, v[164:165]
	global_load_lds_dwordx4 v[244:245], off
	v_lshl_add_u64 v[244:245], s[56:57], 0, v[162:163]
	s_add_i32 m0, s3, 0x2000
	s_nop 0
	global_load_lds_dwordx4 v[244:245], off
	v_lshl_add_u64 v[244:245], s[6:7], 0, v[168:169]
	s_mov_b32 m0, s28
	s_nop 0
	global_load_lds_dwordx4 v[244:245], off
	s_mov_b32 m0, s29
	s_nop 0
	global_load_lds_dwordx4 v[246:247], off
	s_waitcnt vmcnt(8)
	s_waitcnt lgkmcnt(0)
	s_waitcnt lgkmcnt(0)
	v_mfma_f32_16x16x32_bf16 v[62:65], v[130:133], v[196:199], v[62:65]
	v_mfma_f32_16x16x32_bf16 v[58:61], v[138:141], v[196:199], v[58:61]
	v_mfma_f32_16x16x32_bf16 v[54:57], v[130:133], v[220:223], v[54:57]
	v_mfma_f32_16x16x32_bf16 v[50:53], v[138:141], v[220:223], v[50:53]
	s_barrier
	s_setprio 1
	v_mfma_f32_16x16x32_bf16 v[46:49], v[130:133], v[228:231], v[46:49]
	v_mfma_f32_16x16x32_bf16 v[42:45], v[138:141], v[228:231], v[42:45]
	v_mfma_f32_16x16x32_bf16 v[38:41], v[130:133], v[236:239], v[38:41]
	v_mfma_f32_16x16x32_bf16 v[34:37], v[138:141], v[236:239], v[34:37]
	v_mfma_f32_16x16x32_bf16 v[62:65], v[134:137], v[200:203], v[62:65]
	v_mfma_f32_16x16x32_bf16 v[58:61], v[142:145], v[200:203], v[58:61]
	v_mfma_f32_16x16x32_bf16 v[54:57], v[134:137], v[224:227], v[54:57]
	v_mfma_f32_16x16x32_bf16 v[50:53], v[142:145], v[224:227], v[50:53]
	v_mfma_f32_16x16x32_bf16 v[46:49], v[134:137], v[232:235], v[46:49]
	v_mfma_f32_16x16x32_bf16 v[42:45], v[142:145], v[232:235], v[42:45]
	v_mfma_f32_16x16x32_bf16 v[38:41], v[134:137], v[240:243], v[38:41]
	v_mfma_f32_16x16x32_bf16 v[34:37], v[142:145], v[240:243], v[34:37]
	s_setprio 0
	s_setprio 1
	v_mfma_f32_16x16x32_bf16 v[30:33], v[146:149], v[196:199], v[30:33]
	v_mfma_f32_16x16x32_bf16 v[26:29], v[154:157], v[196:199], v[26:29]
	v_mfma_f32_16x16x32_bf16 v[22:25], v[146:149], v[220:223], v[22:25]
	v_mfma_f32_16x16x32_bf16 v[18:21], v[154:157], v[220:223], v[18:21]
	v_mfma_f32_16x16x32_bf16 v[14:17], v[146:149], v[228:231], v[14:17]
	v_mfma_f32_16x16x32_bf16 v[10:13], v[154:157], v[228:231], v[10:13]
	v_mfma_f32_16x16x32_bf16 v[6:9], v[146:149], v[236:239], v[6:9]
	v_mfma_f32_16x16x32_bf16 v[2:5], v[154:157], v[236:239], v[2:5]
	v_mfma_f32_16x16x32_bf16 v[30:33], v[150:153], v[200:203], v[30:33]
	v_mfma_f32_16x16x32_bf16 v[26:29], v[158:161], v[200:203], v[26:29]
	v_mfma_f32_16x16x32_bf16 v[22:25], v[150:153], v[224:227], v[22:25]
	v_mfma_f32_16x16x32_bf16 v[18:21], v[158:161], v[224:227], v[18:21]
	v_mfma_f32_16x16x32_bf16 v[14:17], v[150:153], v[232:235], v[14:17]
	v_mfma_f32_16x16x32_bf16 v[10:13], v[158:161], v[232:235], v[10:13]
	v_mfma_f32_16x16x32_bf16 v[6:9], v[150:153], v[240:243], v[6:9]
	v_mfma_f32_16x16x32_bf16 v[2:5], v[158:161], v[240:243], v[2:5]
	s_setprio 0
	s_barrier
	s_add_i32 s3, 0, 0x18000
	v_add_u32_e32 v0, s3, v206
	s_add_i32 s42, 0, 0x1c000
	ds_read_b128 v[130:133], v0
	ds_read_b128 v[134:137], v0 offset:1024
	ds_read_b128 v[138:141], v0 offset:2048
	ds_read_b128 v[142:145], v0 offset:3072
	v_add_u32_e32 v0, s42, v206
	ds_read_b128 v[146:149], v0
	ds_read_b128 v[150:153], v0 offset:1024
	ds_read_b128 v[154:157], v0 offset:2048
	ds_read_b128 v[158:161], v0 offset:3072
	s_add_u32 s6, s6, 0x80000
	s_addc_u32 s7, s7, 0
	s_mov_b32 m0, s30
	v_lshl_add_u64 v[248:249], s[6:7], 0, v[168:169]
	ds_read_b128 v[196:199], v218 offset:32768
	ds_read_b128 v[200:203], v218 offset:33792
	ds_read_b128 v[220:223], v218 offset:34816
	ds_read_b128 v[224:227], v218 offset:35840
	ds_read_b128 v[228:231], v218 offset:36864
	ds_read_b128 v[232:235], v218 offset:37888
	ds_read_b128 v[236:239], v218 offset:38912
	ds_read_b128 v[240:243], v218 offset:39936
	global_load_lds_dwordx4 v[248:249], off
	v_lshl_add_u64 v[248:249], s[6:7], 0, v[164:165]
	s_mov_b32 m0, s31
	s_nop 0
	global_load_lds_dwordx4 v[248:249], off
	s_waitcnt vmcnt(8)
	s_waitcnt lgkmcnt(0)
	s_waitcnt lgkmcnt(0)
	v_mfma_f32_16x16x32_bf16 v[126:129], v[130:133], v[196:199], v[126:129]
	v_mfma_f32_16x16x32_bf16 v[122:125], v[138:141], v[196:199], v[122:125]
	v_mfma_f32_16x16x32_bf16 v[118:121], v[130:133], v[220:223], v[118:121]
	v_mfma_f32_16x16x32_bf16 v[114:117], v[138:141], v[220:223], v[114:117]
	s_barrier
	s_setprio 1
	v_mfma_f32_16x16x32_bf16 v[110:113], v[130:133], v[228:231], v[110:113]
	v_mfma_f32_16x16x32_bf16 v[106:109], v[138:141], v[228:231], v[106:109]
	v_mfma_f32_16x16x32_bf16 v[102:105], v[130:133], v[236:239], v[102:105]
	v_mfma_f32_16x16x32_bf16 v[98:101], v[138:141], v[236:239], v[98:101]
	v_mfma_f32_16x16x32_bf16 v[126:129], v[134:137], v[200:203], v[126:129]
	v_mfma_f32_16x16x32_bf16 v[122:125], v[142:145], v[200:203], v[122:125]
	v_mfma_f32_16x16x32_bf16 v[118:121], v[134:137], v[224:227], v[118:121]
	v_mfma_f32_16x16x32_bf16 v[114:117], v[142:145], v[224:227], v[114:117]
	v_mfma_f32_16x16x32_bf16 v[110:113], v[134:137], v[232:235], v[110:113]
	v_mfma_f32_16x16x32_bf16 v[106:109], v[142:145], v[232:235], v[106:109]
	v_mfma_f32_16x16x32_bf16 v[102:105], v[134:137], v[240:243], v[102:105]
	v_mfma_f32_16x16x32_bf16 v[98:101], v[142:145], v[240:243], v[98:101]
	s_setprio 0
	s_setprio 1
	v_mfma_f32_16x16x32_bf16 v[94:97], v[146:149], v[196:199], v[94:97]
	v_mfma_f32_16x16x32_bf16 v[90:93], v[154:157], v[196:199], v[90:93]
	v_mfma_f32_16x16x32_bf16 v[86:89], v[146:149], v[220:223], v[86:89]
	v_mfma_f32_16x16x32_bf16 v[82:85], v[154:157], v[220:223], v[82:85]
	v_mfma_f32_16x16x32_bf16 v[78:81], v[146:149], v[228:231], v[78:81]
	v_mfma_f32_16x16x32_bf16 v[74:77], v[154:157], v[228:231], v[74:77]
	v_mfma_f32_16x16x32_bf16 v[70:73], v[146:149], v[236:239], v[70:73]
	v_mfma_f32_16x16x32_bf16 v[66:69], v[154:157], v[236:239], v[66:69]
	v_mfma_f32_16x16x32_bf16 v[94:97], v[150:153], v[200:203], v[94:97]
	v_mfma_f32_16x16x32_bf16 v[90:93], v[158:161], v[200:203], v[90:93]
	v_mfma_f32_16x16x32_bf16 v[86:89], v[150:153], v[224:227], v[86:89]
	v_mfma_f32_16x16x32_bf16 v[82:85], v[158:161], v[224:227], v[82:85]
	v_mfma_f32_16x16x32_bf16 v[78:81], v[150:153], v[232:235], v[78:81]
	v_mfma_f32_16x16x32_bf16 v[74:77], v[158:161], v[232:235], v[74:77]
	v_mfma_f32_16x16x32_bf16 v[70:73], v[150:153], v[240:243], v[70:73]
	v_mfma_f32_16x16x32_bf16 v[66:69], v[158:161], v[240:243], v[66:69]
	s_setprio 0
	s_barrier
	s_add_i32 s3, s3, s2
	v_lshl_add_u64 v[176:177], v[176:177], 0, s[52:53]
	s_mov_b32 m0, s3
	ds_read_b128 v[196:199], v218 offset:49152
	ds_read_b128 v[200:203], v218 offset:50176
	ds_read_b128 v[220:223], v218 offset:51200
	ds_read_b128 v[224:227], v218 offset:52224
	ds_read_b128 v[228:231], v218 offset:53248
	ds_read_b128 v[232:235], v218 offset:54272
	ds_read_b128 v[236:239], v218 offset:55296
	ds_read_b128 v[240:243], v218 offset:56320
	global_load_lds_dwordx4 v[176:177], off
	s_add_i32 m0, s3, 0x2000
	s_add_u32 s4, s4, 0x80080
	v_lshl_add_u64 v[176:177], v[178:179], 0, s[52:53]
	s_addc_u32 s5, s5, 0
	s_add_i32 s3, s42, s2
	global_load_lds_dwordx4 v[176:177], off
	v_lshl_add_u64 v[176:177], s[4:5], 0, v[166:167]
	s_mov_b32 m0, s3
	s_nop 0
	global_load_lds_dwordx4 v[176:177], off
	v_lshl_add_u64 v[176:177], s[4:5], 0, v[162:163]
	s_add_i32 m0, s3, 0x2000
	s_nop 0
	global_load_lds_dwordx4 v[176:177], off
	v_lshl_add_u64 v[176:177], v[244:245], 0, s[52:53]
	s_mov_b32 m0, s35
	s_nop 0
	global_load_lds_dwordx4 v[176:177], off
	v_lshl_add_u64 v[176:177], v[246:247], 0, s[52:53]
	s_mov_b32 m0, s40
	s_nop 0
	global_load_lds_dwordx4 v[176:177], off
	s_waitcnt vmcnt(8)
	s_waitcnt lgkmcnt(0)
	s_waitcnt lgkmcnt(0)
	v_mfma_f32_16x16x32_bf16 v[62:65], v[130:133], v[196:199], v[62:65]
	v_mfma_f32_16x16x32_bf16 v[58:61], v[138:141], v[196:199], v[58:61]
	v_mfma_f32_16x16x32_bf16 v[54:57], v[130:133], v[220:223], v[54:57]
	v_mfma_f32_16x16x32_bf16 v[50:53], v[138:141], v[220:223], v[50:53]
	s_barrier
	s_setprio 1
	v_mfma_f32_16x16x32_bf16 v[46:49], v[130:133], v[228:231], v[46:49]
	v_mfma_f32_16x16x32_bf16 v[42:45], v[138:141], v[228:231], v[42:45]
	v_mfma_f32_16x16x32_bf16 v[38:41], v[130:133], v[236:239], v[38:41]
	v_mfma_f32_16x16x32_bf16 v[34:37], v[138:141], v[236:239], v[34:37]
	v_mfma_f32_16x16x32_bf16 v[62:65], v[134:137], v[200:203], v[62:65]
	v_mfma_f32_16x16x32_bf16 v[58:61], v[142:145], v[200:203], v[58:61]
	v_mfma_f32_16x16x32_bf16 v[54:57], v[134:137], v[224:227], v[54:57]
	v_mfma_f32_16x16x32_bf16 v[50:53], v[142:145], v[224:227], v[50:53]
	v_mfma_f32_16x16x32_bf16 v[46:49], v[134:137], v[232:235], v[46:49]
	v_mfma_f32_16x16x32_bf16 v[42:45], v[142:145], v[232:235], v[42:45]
	v_mfma_f32_16x16x32_bf16 v[38:41], v[134:137], v[240:243], v[38:41]
	v_mfma_f32_16x16x32_bf16 v[34:37], v[142:145], v[240:243], v[34:37]
	s_setprio 0
	s_setprio 1
	v_mfma_f32_16x16x32_bf16 v[30:33], v[146:149], v[196:199], v[30:33]
	v_mfma_f32_16x16x32_bf16 v[26:29], v[154:157], v[196:199], v[26:29]
	v_mfma_f32_16x16x32_bf16 v[22:25], v[146:149], v[220:223], v[22:25]
	v_mfma_f32_16x16x32_bf16 v[18:21], v[154:157], v[220:223], v[18:21]
	v_mfma_f32_16x16x32_bf16 v[14:17], v[146:149], v[228:231], v[14:17]
	v_mfma_f32_16x16x32_bf16 v[10:13], v[154:157], v[228:231], v[10:13]
	v_mfma_f32_16x16x32_bf16 v[6:9], v[146:149], v[236:239], v[6:9]
	v_mfma_f32_16x16x32_bf16 v[2:5], v[154:157], v[236:239], v[2:5]
	v_mfma_f32_16x16x32_bf16 v[30:33], v[150:153], v[200:203], v[30:33]
	v_mfma_f32_16x16x32_bf16 v[26:29], v[158:161], v[200:203], v[26:29]
	v_mfma_f32_16x16x32_bf16 v[22:25], v[150:153], v[224:227], v[22:25]
	v_mfma_f32_16x16x32_bf16 v[18:21], v[158:161], v[224:227], v[18:21]
	v_mfma_f32_16x16x32_bf16 v[14:17], v[150:153], v[232:235], v[14:17]
	v_mfma_f32_16x16x32_bf16 v[10:13], v[158:161], v[232:235], v[10:13]
	v_mfma_f32_16x16x32_bf16 v[6:9], v[150:153], v[240:243], v[6:9]
	v_mfma_f32_16x16x32_bf16 v[2:5], v[158:161], v[240:243], v[2:5]
	s_setprio 0
	s_barrier
	s_add_i32 s46, s46, 2
	s_add_u32 s0, s0, 0x100
	s_addc_u32 s1, s1, 0
	s_add_u32 s26, s26, 0x100
	s_addc_u32 s27, s27, 0
	s_cmp_gt_u32 s46, 29
	s_cbranch_scc0 .LBB0_399
	s_and_b64 vcc, exec, s[14:15]
	s_cbranch_vccz .LBB0_402
	s_barrier

.LBB0_846:
	s_add_u32 s3, s0, 0xfff80080
	s_addc_u32 s18, s1, -1
	s_add_i32 s42, 0, 0x10000
	s_cmp_eq_u32 s41, 28
	s_cselect_b32 s21, s13, s18
	s_cselect_b32 s20, s31, s3
	s_cselect_b32 s19, s11, s40
	s_cselect_b32 s18, s34, s35
	s_add_i32 s3, 0, 0x14000
	v_add_u32_e32 v152, s42, v163
	v_add_u32_e32 v160, s3, v163
	ds_read_b128 v[140:143], v152
	ds_read_b128 v[144:147], v152 offset:1024
	ds_read_b128 v[148:151], v152 offset:2048
	ds_read_b128 v[152:155], v152 offset:3072
	ds_read_b128 v[156:159], v160
	ds_read_b128 v[166:169], v160 offset:1024
	ds_read_b128 v[170:173], v160 offset:2048
	ds_read_b128 v[174:177], v160 offset:3072
	v_lshl_add_u64 v[160:161], s[0:1], 0, v[136:137]
	s_add_i32 m0, s22, 0xc000
	ds_read_b128 v[188:191], v165
	ds_read_b128 v[192:195], v165 offset:1024
	ds_read_b128 v[196:199], v165 offset:2048
	ds_read_b128 v[200:203], v165 offset:3072
	ds_read_b128 v[204:207], v165 offset:4096
	ds_read_b128 v[218:221], v165 offset:5120
	ds_read_b128 v[222:225], v165 offset:6144
	ds_read_b128 v[226:229], v165 offset:7168
	global_load_lds_dwordx4 v[160:161], off
	v_lshl_add_u64 v[160:161], s[0:1], 0, v[138:139]
	s_add_i32 m0, s22, 0xe000
	s_nop 0
	global_load_lds_dwordx4 v[160:161], off
	s_waitcnt vmcnt(8)
	s_waitcnt lgkmcnt(0)
	s_waitcnt lgkmcnt(0)
	v_mfma_f32_16x16x32_bf16 v[126:129], v[140:143], v[188:191], v[126:129]
	v_mfma_f32_16x16x32_bf16 v[122:125], v[148:151], v[188:191], v[122:125]
	v_mfma_f32_16x16x32_bf16 v[110:113], v[140:143], v[196:199], v[110:113]
	v_mfma_f32_16x16x32_bf16 v[106:109], v[148:151], v[196:199], v[106:109]
	s_barrier
	s_setprio 1
	v_mfma_f32_16x16x32_bf16 v[94:97], v[140:143], v[204:207], v[94:97]
	v_mfma_f32_16x16x32_bf16 v[90:93], v[148:151], v[204:207], v[90:93]
	v_mfma_f32_16x16x32_bf16 v[78:81], v[140:143], v[222:225], v[78:81]
	v_mfma_f32_16x16x32_bf16 v[74:77], v[148:151], v[222:225], v[74:77]
	v_mfma_f32_16x16x32_bf16 v[126:129], v[144:147], v[192:195], v[126:129]
	v_mfma_f32_16x16x32_bf16 v[122:125], v[152:155], v[192:195], v[122:125]
	v_mfma_f32_16x16x32_bf16 v[110:113], v[144:147], v[200:203], v[110:113]
	v_mfma_f32_16x16x32_bf16 v[106:109], v[152:155], v[200:203], v[106:109]
	v_mfma_f32_16x16x32_bf16 v[94:97], v[144:147], v[218:221], v[94:97]
	v_mfma_f32_16x16x32_bf16 v[90:93], v[152:155], v[218:221], v[90:93]
	v_mfma_f32_16x16x32_bf16 v[78:81], v[144:147], v[226:229], v[78:81]
	v_mfma_f32_16x16x32_bf16 v[74:77], v[152:155], v[226:229], v[74:77]
	s_setprio 0
	s_setprio 1
	v_mfma_f32_16x16x32_bf16 v[118:121], v[156:159], v[188:191], v[118:121]
	v_mfma_f32_16x16x32_bf16 v[114:117], v[170:173], v[188:191], v[114:117]
	v_mfma_f32_16x16x32_bf16 v[102:105], v[156:159], v[196:199], v[102:105]
	v_mfma_f32_16x16x32_bf16 v[98:101], v[170:173], v[196:199], v[98:101]
	v_mfma_f32_16x16x32_bf16 v[86:89], v[156:159], v[204:207], v[86:89]
	v_mfma_f32_16x16x32_bf16 v[82:85], v[170:173], v[204:207], v[82:85]
	v_mfma_f32_16x16x32_bf16 v[70:73], v[156:159], v[222:225], v[70:73]
	v_mfma_f32_16x16x32_bf16 v[66:69], v[170:173], v[222:225], v[66:69]
	v_mfma_f32_16x16x32_bf16 v[118:121], v[166:169], v[192:195], v[118:121]
	v_mfma_f32_16x16x32_bf16 v[114:117], v[174:177], v[192:195], v[114:117]
	v_mfma_f32_16x16x32_bf16 v[102:105], v[166:169], v[200:203], v[102:105]
	v_mfma_f32_16x16x32_bf16 v[98:101], v[174:177], v[200:203], v[98:101]
	v_mfma_f32_16x16x32_bf16 v[86:89], v[166:169], v[218:221], v[86:89]
	v_mfma_f32_16x16x32_bf16 v[82:85], v[174:177], v[218:221], v[82:85]
	v_mfma_f32_16x16x32_bf16 v[70:73], v[166:169], v[226:229], v[70:73]
	v_mfma_f32_16x16x32_bf16 v[66:69], v[174:177], v[226:229], v[66:69]
	s_setprio 0
	s_barrier
	s_add_i32 s42, s42, s2
	v_lshl_add_u64 v[160:161], s[18:19], 0, v[0:1]
	s_mov_b32 m0, s42
	ds_read_b128 v[188:191], v165 offset:16384
	ds_read_b128 v[192:195], v165 offset:17408
	ds_read_b128 v[196:199], v165 offset:18432
	ds_read_b128 v[200:203], v165 offset:19456
	ds_read_b128 v[204:207], v165 offset:20480
	ds_read_b128 v[218:221], v165 offset:21504
	ds_read_b128 v[222:225], v165 offset:22528
	ds_read_b128 v[226:229], v165 offset:23552
	global_load_lds_dwordx4 v[160:161], off
	s_add_i32 m0, s42, 0x2000
	s_add_u32 s44, s18, 0x80000
	v_lshl_add_u64 v[178:179], s[18:19], 0, v[130:131]
	s_addc_u32 s45, s19, 0
	s_add_i32 s3, s3, s2
	global_load_lds_dwordx4 v[178:179], off
	v_lshl_add_u64 v[180:181], s[44:45], 0, v[0:1]
	s_mov_b32 m0, s3
	v_lshl_add_u64 v[182:183], s[20:21], 0, v[132:133]
	global_load_lds_dwordx4 v[180:181], off
	v_lshl_add_u64 v[180:181], s[44:45], 0, v[130:131]
	s_add_i32 m0, s3, 0x2000
	s_nop 0
	global_load_lds_dwordx4 v[180:181], off
	v_lshl_add_u64 v[180:181], s[20:21], 0, v[134:135]
	s_mov_b32 m0, s22
	s_nop 0
	global_load_lds_dwordx4 v[180:181], off
	s_mov_b32 m0, s23
	s_nop 0
	global_load_lds_dwordx4 v[182:183], off
	s_waitcnt vmcnt(8)
	s_waitcnt lgkmcnt(0)
	s_waitcnt lgkmcnt(0)
	v_mfma_f32_16x16x32_bf16 v[62:65], v[140:143], v[188:191], v[62:65]
	v_mfma_f32_16x16x32_bf16 v[58:61], v[148:151], v[188:191], v[58:61]
	v_mfma_f32_16x16x32_bf16 v[46:49], v[140:143], v[196:199], v[46:49]
	v_mfma_f32_16x16x32_bf16 v[42:45], v[148:151], v[196:199], v[42:45]
	s_barrier
	s_setprio 1
	v_mfma_f32_16x16x32_bf16 v[30:33], v[140:143], v[204:207], v[30:33]
	v_mfma_f32_16x16x32_bf16 v[26:29], v[148:151], v[204:207], v[26:29]
	v_mfma_f32_16x16x32_bf16 v[14:17], v[140:143], v[222:225], v[14:17]
	v_mfma_f32_16x16x32_bf16 v[10:13], v[148:151], v[222:225], v[10:13]
	v_mfma_f32_16x16x32_bf16 v[62:65], v[144:147], v[192:195], v[62:65]
	v_mfma_f32_16x16x32_bf16 v[58:61], v[152:155], v[192:195], v[58:61]
	v_mfma_f32_16x16x32_bf16 v[46:49], v[144:147], v[200:203], v[46:49]
	v_mfma_f32_16x16x32_bf16 v[42:45], v[152:155], v[200:203], v[42:45]
	v_mfma_f32_16x16x32_bf16 v[30:33], v[144:147], v[218:221], v[30:33]
	v_mfma_f32_16x16x32_bf16 v[26:29], v[152:155], v[218:221], v[26:29]
	v_mfma_f32_16x16x32_bf16 v[14:17], v[144:147], v[226:229], v[14:17]
	v_mfma_f32_16x16x32_bf16 v[10:13], v[152:155], v[226:229], v[10:13]
	s_setprio 0
	s_setprio 1
	v_mfma_f32_16x16x32_bf16 v[54:57], v[156:159], v[188:191], v[54:57]
	v_mfma_f32_16x16x32_bf16 v[50:53], v[170:173], v[188:191], v[50:53]
	v_mfma_f32_16x16x32_bf16 v[38:41], v[156:159], v[196:199], v[38:41]
	v_mfma_f32_16x16x32_bf16 v[34:37], v[170:173], v[196:199], v[34:37]
	v_mfma_f32_16x16x32_bf16 v[22:25], v[156:159], v[204:207], v[22:25]
	v_mfma_f32_16x16x32_bf16 v[18:21], v[170:173], v[204:207], v[18:21]
	v_mfma_f32_16x16x32_bf16 v[6:9], v[156:159], v[222:225], v[6:9]
	v_mfma_f32_16x16x32_bf16 v[2:5], v[170:173], v[222:225], v[2:5]
	v_mfma_f32_16x16x32_bf16 v[54:57], v[166:169], v[192:195], v[54:57]
	v_mfma_f32_16x16x32_bf16 v[50:53], v[174:177], v[192:195], v[50:53]
	v_mfma_f32_16x16x32_bf16 v[38:41], v[166:169], v[200:203], v[38:41]
	v_mfma_f32_16x16x32_bf16 v[34:37], v[174:177], v[200:203], v[34:37]
	v_mfma_f32_16x16x32_bf16 v[22:25], v[166:169], v[218:221], v[22:25]
	v_mfma_f32_16x16x32_bf16 v[18:21], v[174:177], v[218:221], v[18:21]
	v_mfma_f32_16x16x32_bf16 v[6:9], v[166:169], v[226:229], v[6:9]
	v_mfma_f32_16x16x32_bf16 v[2:5], v[174:177], v[226:229], v[2:5]
	s_setprio 0
	s_barrier
	s_add_i32 s3, 0, 0x18000
	s_add_i32 s42, 0, 0x1c000
	v_add_u32_e32 v152, s3, v163
	v_add_u32_e32 v174, s42, v163
	ds_read_b128 v[140:143], v152
	ds_read_b128 v[144:147], v152 offset:1024
	ds_read_b128 v[148:151], v152 offset:2048
	ds_read_b128 v[152:155], v152 offset:3072
	ds_read_b128 v[156:159], v174
	ds_read_b128 v[166:169], v174 offset:1024
	ds_read_b128 v[170:173], v174 offset:2048
	ds_read_b128 v[174:177], v174 offset:3072
	s_add_u32 s20, s20, 0x80000
	s_addc_u32 s21, s21, 0
	s_mov_b32 m0, s24
	v_lshl_add_u64 v[184:185], s[20:21], 0, v[134:135]
	ds_read_b128 v[188:191], v165 offset:32768
	ds_read_b128 v[192:195], v165 offset:33792
	ds_read_b128 v[196:199], v165 offset:34816
	ds_read_b128 v[200:203], v165 offset:35840
	ds_read_b128 v[204:207], v165 offset:36864
	ds_read_b128 v[218:221], v165 offset:37888
	ds_read_b128 v[222:225], v165 offset:38912
	ds_read_b128 v[226:229], v165 offset:39936
	global_load_lds_dwordx4 v[184:185], off
	v_lshl_add_u64 v[184:185], s[20:21], 0, v[132:133]
	s_mov_b32 m0, s25
	s_nop 0
	global_load_lds_dwordx4 v[184:185], off
	s_waitcnt vmcnt(8)
	s_waitcnt lgkmcnt(0)
	s_waitcnt lgkmcnt(0)
	v_mfma_f32_16x16x32_bf16 v[126:129], v[140:143], v[188:191], v[126:129]
	v_mfma_f32_16x16x32_bf16 v[122:125], v[148:151], v[188:191], v[122:125]
	v_mfma_f32_16x16x32_bf16 v[110:113], v[140:143], v[196:199], v[110:113]
	v_mfma_f32_16x16x32_bf16 v[106:109], v[148:151], v[196:199], v[106:109]
	s_barrier
	s_setprio 1
	v_mfma_f32_16x16x32_bf16 v[94:97], v[140:143], v[204:207], v[94:97]
	v_mfma_f32_16x16x32_bf16 v[90:93], v[148:151], v[204:207], v[90:93]
	v_mfma_f32_16x16x32_bf16 v[78:81], v[140:143], v[222:225], v[78:81]
	v_mfma_f32_16x16x32_bf16 v[74:77], v[148:151], v[222:225], v[74:77]
	v_mfma_f32_16x16x32_bf16 v[126:129], v[144:147], v[192:195], v[126:129]
	v_mfma_f32_16x16x32_bf16 v[122:125], v[152:155], v[192:195], v[122:125]
	v_mfma_f32_16x16x32_bf16 v[110:113], v[144:147], v[200:203], v[110:113]
	v_mfma_f32_16x16x32_bf16 v[106:109], v[152:155], v[200:203], v[106:109]
	v_mfma_f32_16x16x32_bf16 v[94:97], v[144:147], v[218:221], v[94:97]
	v_mfma_f32_16x16x32_bf16 v[90:93], v[152:155], v[218:221], v[90:93]
	v_mfma_f32_16x16x32_bf16 v[78:81], v[144:147], v[226:229], v[78:81]
	v_mfma_f32_16x16x32_bf16 v[74:77], v[152:155], v[226:229], v[74:77]
	s_setprio 0
	s_setprio 1
	v_mfma_f32_16x16x32_bf16 v[118:121], v[156:159], v[188:191], v[118:121]
	v_mfma_f32_16x16x32_bf16 v[114:117], v[170:173], v[188:191], v[114:117]
	v_mfma_f32_16x16x32_bf16 v[102:105], v[156:159], v[196:199], v[102:105]
	v_mfma_f32_16x16x32_bf16 v[98:101], v[170:173], v[196:199], v[98:101]
	v_mfma_f32_16x16x32_bf16 v[86:89], v[156:159], v[204:207], v[86:89]
	v_mfma_f32_16x16x32_bf16 v[82:85], v[170:173], v[204:207], v[82:85]
	v_mfma_f32_16x16x32_bf16 v[70:73], v[156:159], v[222:225], v[70:73]
	v_mfma_f32_16x16x32_bf16 v[66:69], v[170:173], v[222:225], v[66:69]
	v_mfma_f32_16x16x32_bf16 v[118:121], v[166:169], v[192:195], v[118:121]
	v_mfma_f32_16x16x32_bf16 v[114:117], v[174:177], v[192:195], v[114:117]
	v_mfma_f32_16x16x32_bf16 v[102:105], v[166:169], v[200:203], v[102:105]
	v_mfma_f32_16x16x32_bf16 v[98:101], v[174:177], v[200:203], v[98:101]
	v_mfma_f32_16x16x32_bf16 v[86:89], v[166:169], v[218:221], v[86:89]
	v_mfma_f32_16x16x32_bf16 v[82:85], v[174:177], v[218:221], v[82:85]
	v_mfma_f32_16x16x32_bf16 v[70:73], v[166:169], v[226:229], v[70:73]
	v_mfma_f32_16x16x32_bf16 v[66:69], v[174:177], v[226:229], v[66:69]
	s_setprio 0
	s_barrier
	s_add_i32 s3, s3, s2
	v_lshl_add_u64 v[160:161], v[160:161], 0, s[52:53]
	s_mov_b32 m0, s3
	ds_read_b128 v[188:191], v165 offset:49152
	ds_read_b128 v[192:195], v165 offset:50176
	ds_read_b128 v[196:199], v165 offset:51200
	ds_read_b128 v[200:203], v165 offset:52224
	ds_read_b128 v[204:207], v165 offset:53248
	ds_read_b128 v[218:221], v165 offset:54272
	ds_read_b128 v[222:225], v165 offset:55296
	ds_read_b128 v[226:229], v165 offset:56320
	global_load_lds_dwordx4 v[160:161], off
	s_add_i32 m0, s3, 0x2000
	s_add_u32 s18, s18, 0x80080
	v_lshl_add_u64 v[160:161], v[178:179], 0, s[52:53]
	s_addc_u32 s19, s19, 0
	s_add_i32 s3, s42, s2
	global_load_lds_dwordx4 v[160:161], off
	v_lshl_add_u64 v[160:161], s[18:19], 0, v[0:1]
	s_mov_b32 m0, s3
	s_nop 0
	global_load_lds_dwordx4 v[160:161], off
	v_lshl_add_u64 v[160:161], s[18:19], 0, v[130:131]
	s_add_i32 m0, s3, 0x2000
	s_nop 0
	global_load_lds_dwordx4 v[160:161], off
	v_lshl_add_u64 v[160:161], v[180:181], 0, s[52:53]
	s_mov_b32 m0, s26
	s_nop 0
	global_load_lds_dwordx4 v[160:161], off
	v_lshl_add_u64 v[160:161], v[182:183], 0, s[52:53]
	s_mov_b32 m0, s27
	s_nop 0
	global_load_lds_dwordx4 v[160:161], off
	s_waitcnt vmcnt(8)
	s_waitcnt lgkmcnt(0)
	s_waitcnt lgkmcnt(0)
	v_mfma_f32_16x16x32_bf16 v[62:65], v[140:143], v[188:191], v[62:65]
	v_mfma_f32_16x16x32_bf16 v[58:61], v[148:151], v[188:191], v[58:61]
	v_mfma_f32_16x16x32_bf16 v[46:49], v[140:143], v[196:199], v[46:49]
	v_mfma_f32_16x16x32_bf16 v[42:45], v[148:151], v[196:199], v[42:45]
	s_barrier
	s_setprio 1
	v_mfma_f32_16x16x32_bf16 v[30:33], v[140:143], v[204:207], v[30:33]
	v_mfma_f32_16x16x32_bf16 v[26:29], v[148:151], v[204:207], v[26:29]
	v_mfma_f32_16x16x32_bf16 v[14:17], v[140:143], v[222:225], v[14:17]
	v_mfma_f32_16x16x32_bf16 v[10:13], v[148:151], v[222:225], v[10:13]
	v_mfma_f32_16x16x32_bf16 v[62:65], v[144:147], v[192:195], v[62:65]
	v_mfma_f32_16x16x32_bf16 v[58:61], v[152:155], v[192:195], v[58:61]
	v_mfma_f32_16x16x32_bf16 v[46:49], v[144:147], v[200:203], v[46:49]
	v_mfma_f32_16x16x32_bf16 v[42:45], v[152:155], v[200:203], v[42:45]
	v_mfma_f32_16x16x32_bf16 v[30:33], v[144:147], v[218:221], v[30:33]
	v_mfma_f32_16x16x32_bf16 v[26:29], v[152:155], v[218:221], v[26:29]
	v_mfma_f32_16x16x32_bf16 v[14:17], v[144:147], v[226:229], v[14:17]
	v_mfma_f32_16x16x32_bf16 v[10:13], v[152:155], v[226:229], v[10:13]
	s_setprio 0
	s_setprio 1
	v_mfma_f32_16x16x32_bf16 v[54:57], v[156:159], v[188:191], v[54:57]
	v_mfma_f32_16x16x32_bf16 v[50:53], v[170:173], v[188:191], v[50:53]
	v_mfma_f32_16x16x32_bf16 v[38:41], v[156:159], v[196:199], v[38:41]
	v_mfma_f32_16x16x32_bf16 v[34:37], v[170:173], v[196:199], v[34:37]
	v_mfma_f32_16x16x32_bf16 v[22:25], v[156:159], v[204:207], v[22:25]
	v_mfma_f32_16x16x32_bf16 v[18:21], v[170:173], v[204:207], v[18:21]
	v_mfma_f32_16x16x32_bf16 v[6:9], v[156:159], v[222:225], v[6:9]
	v_mfma_f32_16x16x32_bf16 v[2:5], v[170:173], v[222:225], v[2:5]
	v_mfma_f32_16x16x32_bf16 v[54:57], v[166:169], v[192:195], v[54:57]
	v_mfma_f32_16x16x32_bf16 v[50:53], v[174:177], v[192:195], v[50:53]
	v_mfma_f32_16x16x32_bf16 v[38:41], v[166:169], v[200:203], v[38:41]
	v_mfma_f32_16x16x32_bf16 v[34:37], v[174:177], v[200:203], v[34:37]
	v_mfma_f32_16x16x32_bf16 v[22:25], v[166:169], v[218:221], v[22:25]
	v_mfma_f32_16x16x32_bf16 v[18:21], v[174:177], v[218:221], v[18:21]
	v_mfma_f32_16x16x32_bf16 v[6:9], v[166:169], v[226:229], v[6:9]
	v_mfma_f32_16x16x32_bf16 v[2:5], v[174:177], v[226:229], v[2:5]
	s_setprio 0
	s_barrier
	s_add_i32 s41, s41, 2
	s_add_u32 s0, s0, 0x100
	s_addc_u32 s1, s1, 0
	s_add_u32 s35, s35, 0x100
	s_addc_u32 s40, s40, 0
	s_cmp_gt_u32 s41, 29
	s_cbranch_scc0 .LBB0_846
	s_and_b64 vcc, exec, s[8:9]
	s_movk_i32 s40, 0x4000
	s_movk_i32 s41, 0x6000
	s_cbranch_vccz .LBB0_849
	s_barrier

.LBB0_959:
	s_add_u32 s3, s16, 0xfff80080
	s_addc_u32 s18, s17, -1
	s_add_i32 s42, 0, 0x10000
	s_cmp_eq_u32 s46, 28
	s_cselect_b32 s21, s11, s18
	s_cselect_b32 s20, s40, s3
	v_add_u32_e32 v140, s42, v143
	s_cselect_b32 s19, s9, s45
	s_cselect_b32 s18, s41, s44
	s_add_i32 s3, 0, 0x14000
	ds_read_b128 v[146:149], v140
	ds_read_b128 v[150:153], v140 offset:1024
	ds_read_b128 v[154:157], v140 offset:2048
	ds_read_b128 v[158:161], v140 offset:3072
	v_add_u32_e32 v140, s3, v143
	ds_read_b128 v[162:165], v140
	ds_read_b128 v[166:169], v140 offset:1024
	ds_read_b128 v[170:173], v140 offset:2048
	ds_read_b128 v[174:177], v140 offset:3072
	v_lshl_add_u64 v[140:141], s[16:17], 0, v[136:137]
	s_add_i32 m0, s25, 0xc000
	ds_read_b128 v[188:191], v145
	ds_read_b128 v[192:195], v145 offset:1024
	ds_read_b128 v[196:199], v145 offset:2048
	ds_read_b128 v[200:203], v145 offset:3072
	ds_read_b128 v[204:207], v145 offset:4096
	ds_read_b128 v[218:221], v145 offset:5120
	ds_read_b128 v[222:225], v145 offset:6144
	ds_read_b128 v[226:229], v145 offset:7168
	global_load_lds_dwordx4 v[140:141], off
	v_lshl_add_u64 v[140:141], s[16:17], 0, v[138:139]
	s_add_i32 m0, s25, 0xe000
	s_nop 0
	global_load_lds_dwordx4 v[140:141], off
	s_waitcnt vmcnt(8)
	s_waitcnt lgkmcnt(0)
	s_waitcnt lgkmcnt(0)
	v_mfma_f32_16x16x32_bf16 v[126:129], v[146:149], v[188:191], v[126:129]
	v_mfma_f32_16x16x32_bf16 v[122:125], v[154:157], v[188:191], v[122:125]
	v_mfma_f32_16x16x32_bf16 v[110:113], v[146:149], v[196:199], v[110:113]
	v_mfma_f32_16x16x32_bf16 v[106:109], v[154:157], v[196:199], v[106:109]
	s_barrier
	s_setprio 1
	v_mfma_f32_16x16x32_bf16 v[94:97], v[146:149], v[204:207], v[94:97]
	v_mfma_f32_16x16x32_bf16 v[90:93], v[154:157], v[204:207], v[90:93]
	v_mfma_f32_16x16x32_bf16 v[78:81], v[146:149], v[222:225], v[78:81]
	v_mfma_f32_16x16x32_bf16 v[74:77], v[154:157], v[222:225], v[74:77]
	v_mfma_f32_16x16x32_bf16 v[126:129], v[150:153], v[192:195], v[126:129]
	v_mfma_f32_16x16x32_bf16 v[122:125], v[158:161], v[192:195], v[122:125]
	v_mfma_f32_16x16x32_bf16 v[110:113], v[150:153], v[200:203], v[110:113]
	v_mfma_f32_16x16x32_bf16 v[106:109], v[158:161], v[200:203], v[106:109]
	v_mfma_f32_16x16x32_bf16 v[94:97], v[150:153], v[218:221], v[94:97]
	v_mfma_f32_16x16x32_bf16 v[90:93], v[158:161], v[218:221], v[90:93]
	v_mfma_f32_16x16x32_bf16 v[78:81], v[150:153], v[226:229], v[78:81]
	v_mfma_f32_16x16x32_bf16 v[74:77], v[158:161], v[226:229], v[74:77]
	s_setprio 0
	s_setprio 1
	v_mfma_f32_16x16x32_bf16 v[118:121], v[162:165], v[188:191], v[118:121]
	v_mfma_f32_16x16x32_bf16 v[114:117], v[170:173], v[188:191], v[114:117]
	v_mfma_f32_16x16x32_bf16 v[102:105], v[162:165], v[196:199], v[102:105]
	v_mfma_f32_16x16x32_bf16 v[98:101], v[170:173], v[196:199], v[98:101]
	v_mfma_f32_16x16x32_bf16 v[86:89], v[162:165], v[204:207], v[86:89]
	v_mfma_f32_16x16x32_bf16 v[82:85], v[170:173], v[204:207], v[82:85]
	v_mfma_f32_16x16x32_bf16 v[70:73], v[162:165], v[222:225], v[70:73]
	v_mfma_f32_16x16x32_bf16 v[66:69], v[170:173], v[222:225], v[66:69]
	v_mfma_f32_16x16x32_bf16 v[118:121], v[166:169], v[192:195], v[118:121]
	v_mfma_f32_16x16x32_bf16 v[114:117], v[174:177], v[192:195], v[114:117]
	v_mfma_f32_16x16x32_bf16 v[102:105], v[166:169], v[200:203], v[102:105]
	v_mfma_f32_16x16x32_bf16 v[98:101], v[174:177], v[200:203], v[98:101]
	v_mfma_f32_16x16x32_bf16 v[86:89], v[166:169], v[218:221], v[86:89]
	v_mfma_f32_16x16x32_bf16 v[82:85], v[174:177], v[218:221], v[82:85]
	v_mfma_f32_16x16x32_bf16 v[70:73], v[166:169], v[226:229], v[70:73]
	v_mfma_f32_16x16x32_bf16 v[66:69], v[174:177], v[226:229], v[66:69]
	s_setprio 0
	s_barrier
	s_add_i32 s42, s42, s24
	v_lshl_add_u64 v[140:141], s[18:19], 0, v[0:1]
	s_mov_b32 m0, s42
	ds_read_b128 v[188:191], v145 offset:16384
	ds_read_b128 v[192:195], v145 offset:17408
	ds_read_b128 v[196:199], v145 offset:18432
	ds_read_b128 v[200:203], v145 offset:19456
	ds_read_b128 v[204:207], v145 offset:20480
	ds_read_b128 v[218:221], v145 offset:21504
	ds_read_b128 v[222:225], v145 offset:22528
	ds_read_b128 v[226:229], v145 offset:23552
	global_load_lds_dwordx4 v[140:141], off
	s_add_i32 m0, s42, 0x2000
	s_add_u32 s56, s18, 0x80000
	v_lshl_add_u64 v[178:179], s[18:19], 0, v[130:131]
	s_addc_u32 s57, s19, 0
	s_add_i32 s3, s3, s24
	global_load_lds_dwordx4 v[178:179], off
	v_lshl_add_u64 v[180:181], s[56:57], 0, v[0:1]
	s_mov_b32 m0, s3
	v_lshl_add_u64 v[182:183], s[20:21], 0, v[132:133]
	global_load_lds_dwordx4 v[180:181], off
	v_lshl_add_u64 v[180:181], s[56:57], 0, v[130:131]
	s_add_i32 m0, s3, 0x2000
	s_nop 0
	global_load_lds_dwordx4 v[180:181], off
	v_lshl_add_u64 v[180:181], s[20:21], 0, v[134:135]
	s_mov_b32 m0, s25
	s_nop 0
	global_load_lds_dwordx4 v[180:181], off
	s_mov_b32 m0, s26
	s_nop 0
	global_load_lds_dwordx4 v[182:183], off
	s_waitcnt vmcnt(8)
	s_waitcnt lgkmcnt(0)
	s_waitcnt lgkmcnt(0)
	v_mfma_f32_16x16x32_bf16 v[62:65], v[146:149], v[188:191], v[62:65]
	v_mfma_f32_16x16x32_bf16 v[58:61], v[154:157], v[188:191], v[58:61]
	v_mfma_f32_16x16x32_bf16 v[46:49], v[146:149], v[196:199], v[46:49]
	v_mfma_f32_16x16x32_bf16 v[42:45], v[154:157], v[196:199], v[42:45]
	s_barrier
	s_setprio 1
	v_mfma_f32_16x16x32_bf16 v[30:33], v[146:149], v[204:207], v[30:33]
	v_mfma_f32_16x16x32_bf16 v[26:29], v[154:157], v[204:207], v[26:29]
	v_mfma_f32_16x16x32_bf16 v[14:17], v[146:149], v[222:225], v[14:17]
	v_mfma_f32_16x16x32_bf16 v[10:13], v[154:157], v[222:225], v[10:13]
	v_mfma_f32_16x16x32_bf16 v[62:65], v[150:153], v[192:195], v[62:65]
	v_mfma_f32_16x16x32_bf16 v[58:61], v[158:161], v[192:195], v[58:61]
	v_mfma_f32_16x16x32_bf16 v[46:49], v[150:153], v[200:203], v[46:49]
	v_mfma_f32_16x16x32_bf16 v[42:45], v[158:161], v[200:203], v[42:45]
	v_mfma_f32_16x16x32_bf16 v[30:33], v[150:153], v[218:221], v[30:33]
	v_mfma_f32_16x16x32_bf16 v[26:29], v[158:161], v[218:221], v[26:29]
	v_mfma_f32_16x16x32_bf16 v[14:17], v[150:153], v[226:229], v[14:17]
	v_mfma_f32_16x16x32_bf16 v[10:13], v[158:161], v[226:229], v[10:13]
	s_setprio 0
	s_setprio 1
	v_mfma_f32_16x16x32_bf16 v[54:57], v[162:165], v[188:191], v[54:57]
	v_mfma_f32_16x16x32_bf16 v[50:53], v[170:173], v[188:191], v[50:53]
	v_mfma_f32_16x16x32_bf16 v[38:41], v[162:165], v[196:199], v[38:41]
	v_mfma_f32_16x16x32_bf16 v[34:37], v[170:173], v[196:199], v[34:37]
	v_mfma_f32_16x16x32_bf16 v[22:25], v[162:165], v[204:207], v[22:25]
	v_mfma_f32_16x16x32_bf16 v[18:21], v[170:173], v[204:207], v[18:21]
	v_mfma_f32_16x16x32_bf16 v[6:9], v[162:165], v[222:225], v[6:9]
	v_mfma_f32_16x16x32_bf16 v[2:5], v[170:173], v[222:225], v[2:5]
	v_mfma_f32_16x16x32_bf16 v[54:57], v[166:169], v[192:195], v[54:57]
	v_mfma_f32_16x16x32_bf16 v[50:53], v[174:177], v[192:195], v[50:53]
	v_mfma_f32_16x16x32_bf16 v[38:41], v[166:169], v[200:203], v[38:41]
	v_mfma_f32_16x16x32_bf16 v[34:37], v[174:177], v[200:203], v[34:37]
	v_mfma_f32_16x16x32_bf16 v[22:25], v[166:169], v[218:221], v[22:25]
	v_mfma_f32_16x16x32_bf16 v[18:21], v[174:177], v[218:221], v[18:21]
	v_mfma_f32_16x16x32_bf16 v[6:9], v[166:169], v[226:229], v[6:9]
	v_mfma_f32_16x16x32_bf16 v[2:5], v[174:177], v[226:229], v[2:5]
	s_setprio 0
	s_barrier
	s_add_i32 s3, 0, 0x18000
	s_add_i32 s42, 0, 0x1c000
	v_add_u32_e32 v158, s3, v143
	v_add_u32_e32 v174, s42, v143
	ds_read_b128 v[146:149], v158
	ds_read_b128 v[150:153], v158 offset:1024
	ds_read_b128 v[154:157], v158 offset:2048
	ds_read_b128 v[158:161], v158 offset:3072
	ds_read_b128 v[162:165], v174
	ds_read_b128 v[166:169], v174 offset:1024
	ds_read_b128 v[170:173], v174 offset:2048
	ds_read_b128 v[174:177], v174 offset:3072
	s_add_u32 s20, s20, 0x80000
	s_addc_u32 s21, s21, 0
	s_mov_b32 m0, s27
	v_lshl_add_u64 v[184:185], s[20:21], 0, v[134:135]
	ds_read_b128 v[188:191], v145 offset:32768
	ds_read_b128 v[192:195], v145 offset:33792
	ds_read_b128 v[196:199], v145 offset:34816
	ds_read_b128 v[200:203], v145 offset:35840
	ds_read_b128 v[204:207], v145 offset:36864
	ds_read_b128 v[218:221], v145 offset:37888
	ds_read_b128 v[222:225], v145 offset:38912
	ds_read_b128 v[226:229], v145 offset:39936
	global_load_lds_dwordx4 v[184:185], off
	v_lshl_add_u64 v[184:185], s[20:21], 0, v[132:133]
	s_mov_b32 m0, s28
	s_nop 0
	global_load_lds_dwordx4 v[184:185], off
	s_waitcnt vmcnt(8)
	s_waitcnt lgkmcnt(0)
	s_waitcnt lgkmcnt(0)
	v_mfma_f32_16x16x32_bf16 v[126:129], v[146:149], v[188:191], v[126:129]
	v_mfma_f32_16x16x32_bf16 v[122:125], v[154:157], v[188:191], v[122:125]
	v_mfma_f32_16x16x32_bf16 v[110:113], v[146:149], v[196:199], v[110:113]
	v_mfma_f32_16x16x32_bf16 v[106:109], v[154:157], v[196:199], v[106:109]
	s_barrier
	s_setprio 1
	v_mfma_f32_16x16x32_bf16 v[94:97], v[146:149], v[204:207], v[94:97]
	v_mfma_f32_16x16x32_bf16 v[90:93], v[154:157], v[204:207], v[90:93]
	v_mfma_f32_16x16x32_bf16 v[78:81], v[146:149], v[222:225], v[78:81]
	v_mfma_f32_16x16x32_bf16 v[74:77], v[154:157], v[222:225], v[74:77]
	v_mfma_f32_16x16x32_bf16 v[126:129], v[150:153], v[192:195], v[126:129]
	v_mfma_f32_16x16x32_bf16 v[122:125], v[158:161], v[192:195], v[122:125]
	v_mfma_f32_16x16x32_bf16 v[110:113], v[150:153], v[200:203], v[110:113]
	v_mfma_f32_16x16x32_bf16 v[106:109], v[158:161], v[200:203], v[106:109]
	v_mfma_f32_16x16x32_bf16 v[94:97], v[150:153], v[218:221], v[94:97]
	v_mfma_f32_16x16x32_bf16 v[90:93], v[158:161], v[218:221], v[90:93]
	v_mfma_f32_16x16x32_bf16 v[78:81], v[150:153], v[226:229], v[78:81]
	v_mfma_f32_16x16x32_bf16 v[74:77], v[158:161], v[226:229], v[74:77]
	s_setprio 0
	s_setprio 1
	v_mfma_f32_16x16x32_bf16 v[118:121], v[162:165], v[188:191], v[118:121]
	v_mfma_f32_16x16x32_bf16 v[114:117], v[170:173], v[188:191], v[114:117]
	v_mfma_f32_16x16x32_bf16 v[102:105], v[162:165], v[196:199], v[102:105]
	v_mfma_f32_16x16x32_bf16 v[98:101], v[170:173], v[196:199], v[98:101]
	v_mfma_f32_16x16x32_bf16 v[86:89], v[162:165], v[204:207], v[86:89]
	v_mfma_f32_16x16x32_bf16 v[82:85], v[170:173], v[204:207], v[82:85]
	v_mfma_f32_16x16x32_bf16 v[70:73], v[162:165], v[222:225], v[70:73]
	v_mfma_f32_16x16x32_bf16 v[66:69], v[170:173], v[222:225], v[66:69]
	v_mfma_f32_16x16x32_bf16 v[118:121], v[166:169], v[192:195], v[118:121]
	v_mfma_f32_16x16x32_bf16 v[114:117], v[174:177], v[192:195], v[114:117]
	v_mfma_f32_16x16x32_bf16 v[102:105], v[166:169], v[200:203], v[102:105]
	v_mfma_f32_16x16x32_bf16 v[98:101], v[174:177], v[200:203], v[98:101]
	v_mfma_f32_16x16x32_bf16 v[86:89], v[166:169], v[218:221], v[86:89]
	v_mfma_f32_16x16x32_bf16 v[82:85], v[174:177], v[218:221], v[82:85]
	v_mfma_f32_16x16x32_bf16 v[70:73], v[166:169], v[226:229], v[70:73]
	v_mfma_f32_16x16x32_bf16 v[66:69], v[174:177], v[226:229], v[66:69]
	s_setprio 0
	s_barrier
	s_add_i32 s3, s3, s24
	v_lshl_add_u64 v[140:141], v[140:141], 0, s[52:53]
	s_mov_b32 m0, s3
	ds_read_b128 v[188:191], v145 offset:49152
	ds_read_b128 v[192:195], v145 offset:50176
	ds_read_b128 v[196:199], v145 offset:51200
	ds_read_b128 v[200:203], v145 offset:52224
	ds_read_b128 v[204:207], v145 offset:53248
	ds_read_b128 v[218:221], v145 offset:54272
	ds_read_b128 v[222:225], v145 offset:55296
	ds_read_b128 v[226:229], v145 offset:56320
	global_load_lds_dwordx4 v[140:141], off
	s_add_i32 m0, s3, 0x2000
	s_add_u32 s18, s18, 0x80080
	v_lshl_add_u64 v[140:141], v[178:179], 0, s[52:53]
	s_addc_u32 s19, s19, 0
	s_add_i32 s3, s42, s24
	global_load_lds_dwordx4 v[140:141], off
	v_lshl_add_u64 v[140:141], s[18:19], 0, v[0:1]
	s_mov_b32 m0, s3
	s_nop 0
	global_load_lds_dwordx4 v[140:141], off
	v_lshl_add_u64 v[140:141], s[18:19], 0, v[130:131]
	s_add_i32 m0, s3, 0x2000
	s_nop 0
	global_load_lds_dwordx4 v[140:141], off
	v_lshl_add_u64 v[140:141], v[180:181], 0, s[52:53]
	s_mov_b32 m0, s29
	s_nop 0
	global_load_lds_dwordx4 v[140:141], off
	v_lshl_add_u64 v[140:141], v[182:183], 0, s[52:53]
	s_mov_b32 m0, s30
	s_nop 0
	global_load_lds_dwordx4 v[140:141], off
	s_waitcnt vmcnt(8)
	s_waitcnt lgkmcnt(0)
	s_waitcnt lgkmcnt(0)
	v_mfma_f32_16x16x32_bf16 v[62:65], v[146:149], v[188:191], v[62:65]
	v_mfma_f32_16x16x32_bf16 v[58:61], v[154:157], v[188:191], v[58:61]
	v_mfma_f32_16x16x32_bf16 v[46:49], v[146:149], v[196:199], v[46:49]
	v_mfma_f32_16x16x32_bf16 v[42:45], v[154:157], v[196:199], v[42:45]
	s_barrier
	s_setprio 1
	v_mfma_f32_16x16x32_bf16 v[30:33], v[146:149], v[204:207], v[30:33]
	v_mfma_f32_16x16x32_bf16 v[26:29], v[154:157], v[204:207], v[26:29]
	v_mfma_f32_16x16x32_bf16 v[14:17], v[146:149], v[222:225], v[14:17]
	v_mfma_f32_16x16x32_bf16 v[10:13], v[154:157], v[222:225], v[10:13]
	v_mfma_f32_16x16x32_bf16 v[62:65], v[150:153], v[192:195], v[62:65]
	v_mfma_f32_16x16x32_bf16 v[58:61], v[158:161], v[192:195], v[58:61]
	v_mfma_f32_16x16x32_bf16 v[46:49], v[150:153], v[200:203], v[46:49]
	v_mfma_f32_16x16x32_bf16 v[42:45], v[158:161], v[200:203], v[42:45]
	v_mfma_f32_16x16x32_bf16 v[30:33], v[150:153], v[218:221], v[30:33]
	v_mfma_f32_16x16x32_bf16 v[26:29], v[158:161], v[218:221], v[26:29]
	v_mfma_f32_16x16x32_bf16 v[14:17], v[150:153], v[226:229], v[14:17]
	v_mfma_f32_16x16x32_bf16 v[10:13], v[158:161], v[226:229], v[10:13]
	s_setprio 0
	s_setprio 1
	v_mfma_f32_16x16x32_bf16 v[54:57], v[162:165], v[188:191], v[54:57]
	v_mfma_f32_16x16x32_bf16 v[50:53], v[170:173], v[188:191], v[50:53]
	v_mfma_f32_16x16x32_bf16 v[38:41], v[162:165], v[196:199], v[38:41]
	v_mfma_f32_16x16x32_bf16 v[34:37], v[170:173], v[196:199], v[34:37]
	v_mfma_f32_16x16x32_bf16 v[22:25], v[162:165], v[204:207], v[22:25]
	v_mfma_f32_16x16x32_bf16 v[18:21], v[170:173], v[204:207], v[18:21]
	v_mfma_f32_16x16x32_bf16 v[6:9], v[162:165], v[222:225], v[6:9]
	v_mfma_f32_16x16x32_bf16 v[2:5], v[170:173], v[222:225], v[2:5]
	v_mfma_f32_16x16x32_bf16 v[54:57], v[166:169], v[192:195], v[54:57]
	v_mfma_f32_16x16x32_bf16 v[50:53], v[174:177], v[192:195], v[50:53]
	v_mfma_f32_16x16x32_bf16 v[38:41], v[166:169], v[200:203], v[38:41]
	v_mfma_f32_16x16x32_bf16 v[34:37], v[174:177], v[200:203], v[34:37]
	v_mfma_f32_16x16x32_bf16 v[22:25], v[166:169], v[218:221], v[22:25]
	v_mfma_f32_16x16x32_bf16 v[18:21], v[174:177], v[218:221], v[18:21]
	v_mfma_f32_16x16x32_bf16 v[6:9], v[166:169], v[226:229], v[6:9]
	v_mfma_f32_16x16x32_bf16 v[2:5], v[174:177], v[226:229], v[2:5]
	s_setprio 0
	s_barrier
	s_add_i32 s46, s46, 2
	s_add_u32 s16, s16, 0x100
	s_addc_u32 s17, s17, 0
	s_add_u32 s44, s44, 0x100
	s_addc_u32 s45, s45, 0
	s_cmp_gt_u32 s46, 29
	s_cbranch_scc0 .LBB0_959
	s_and_b64 vcc, exec, s[6:7]
	s_movk_i32 s40, 0x4000
	s_movk_i32 s41, 0x6000
	s_mov_b32 s44, 0x8000
	s_mov_b32 s45, 0xa000
	s_cbranch_vccz .LBB0_962
	s_barrier

.LBB0_1024:
	s_add_u32 s3, s20, 0xffe00080
	s_addc_u32 s22, s21, -1
	s_add_i32 s42, 0, 0x10000
	s_cmpk_eq_i32 s57, 0x7c
	s_cselect_b32 s25, s15, s22
	s_cselect_b32 s24, s45, s3
	s_cselect_b32 s23, s13, s56
	s_cselect_b32 s22, s46, s47
	s_add_i32 s3, 0, 0x14000
	v_add_u32_e32 v152, s42, v163
	v_add_u32_e32 v160, s3, v163
	ds_read_b128 v[140:143], v152
	ds_read_b128 v[144:147], v152 offset:1024
	ds_read_b128 v[148:151], v152 offset:2048
	ds_read_b128 v[152:155], v152 offset:3072
	ds_read_b128 v[156:159], v160
	ds_read_b128 v[166:169], v160 offset:1024
	ds_read_b128 v[170:173], v160 offset:2048
	ds_read_b128 v[174:177], v160 offset:3072
	v_lshl_add_u64 v[160:161], s[20:21], 0, v[136:137]
	s_add_i32 m0, s28, 0xc000
	ds_read_b128 v[188:191], v165
	ds_read_b128 v[192:195], v165 offset:1024
	ds_read_b128 v[196:199], v165 offset:2048
	ds_read_b128 v[200:203], v165 offset:3072
	ds_read_b128 v[204:207], v165 offset:4096
	ds_read_b128 v[218:221], v165 offset:5120
	ds_read_b128 v[222:225], v165 offset:6144
	ds_read_b128 v[226:229], v165 offset:7168
	global_load_lds_dwordx4 v[160:161], off
	v_lshl_add_u64 v[160:161], s[20:21], 0, v[138:139]
	s_add_i32 m0, s28, 0xe000
	s_nop 0
	global_load_lds_dwordx4 v[160:161], off
	s_waitcnt vmcnt(8)
	s_waitcnt lgkmcnt(0)
	s_waitcnt lgkmcnt(0)
	v_mfma_f32_16x16x32_bf16 v[126:129], v[140:143], v[188:191], v[126:129]
	v_mfma_f32_16x16x32_bf16 v[122:125], v[148:151], v[188:191], v[122:125]
	v_mfma_f32_16x16x32_bf16 v[110:113], v[140:143], v[196:199], v[110:113]
	v_mfma_f32_16x16x32_bf16 v[106:109], v[148:151], v[196:199], v[106:109]
	s_barrier
	s_setprio 1
	v_mfma_f32_16x16x32_bf16 v[94:97], v[140:143], v[204:207], v[94:97]
	v_mfma_f32_16x16x32_bf16 v[90:93], v[148:151], v[204:207], v[90:93]
	v_mfma_f32_16x16x32_bf16 v[78:81], v[140:143], v[222:225], v[78:81]
	v_mfma_f32_16x16x32_bf16 v[74:77], v[148:151], v[222:225], v[74:77]
	v_mfma_f32_16x16x32_bf16 v[126:129], v[144:147], v[192:195], v[126:129]
	v_mfma_f32_16x16x32_bf16 v[122:125], v[152:155], v[192:195], v[122:125]
	v_mfma_f32_16x16x32_bf16 v[110:113], v[144:147], v[200:203], v[110:113]
	v_mfma_f32_16x16x32_bf16 v[106:109], v[152:155], v[200:203], v[106:109]
	v_mfma_f32_16x16x32_bf16 v[94:97], v[144:147], v[218:221], v[94:97]
	v_mfma_f32_16x16x32_bf16 v[90:93], v[152:155], v[218:221], v[90:93]
	v_mfma_f32_16x16x32_bf16 v[78:81], v[144:147], v[226:229], v[78:81]
	v_mfma_f32_16x16x32_bf16 v[74:77], v[152:155], v[226:229], v[74:77]
	s_setprio 0
	s_setprio 1
	v_mfma_f32_16x16x32_bf16 v[118:121], v[156:159], v[188:191], v[118:121]
	v_mfma_f32_16x16x32_bf16 v[114:117], v[170:173], v[188:191], v[114:117]
	v_mfma_f32_16x16x32_bf16 v[102:105], v[156:159], v[196:199], v[102:105]
	v_mfma_f32_16x16x32_bf16 v[98:101], v[170:173], v[196:199], v[98:101]
	v_mfma_f32_16x16x32_bf16 v[86:89], v[156:159], v[204:207], v[86:89]
	v_mfma_f32_16x16x32_bf16 v[82:85], v[170:173], v[204:207], v[82:85]
	v_mfma_f32_16x16x32_bf16 v[70:73], v[156:159], v[222:225], v[70:73]
	v_mfma_f32_16x16x32_bf16 v[66:69], v[170:173], v[222:225], v[66:69]
	v_mfma_f32_16x16x32_bf16 v[118:121], v[166:169], v[192:195], v[118:121]
	v_mfma_f32_16x16x32_bf16 v[114:117], v[174:177], v[192:195], v[114:117]
	v_mfma_f32_16x16x32_bf16 v[102:105], v[166:169], v[200:203], v[102:105]
	v_mfma_f32_16x16x32_bf16 v[98:101], v[174:177], v[200:203], v[98:101]
	v_mfma_f32_16x16x32_bf16 v[86:89], v[166:169], v[218:221], v[86:89]
	v_mfma_f32_16x16x32_bf16 v[82:85], v[174:177], v[218:221], v[82:85]
	v_mfma_f32_16x16x32_bf16 v[70:73], v[166:169], v[226:229], v[70:73]
	v_mfma_f32_16x16x32_bf16 v[66:69], v[174:177], v[226:229], v[66:69]
	s_setprio 0
	s_barrier
	s_add_i32 s42, s42, s27
	v_lshl_add_u64 v[160:161], s[22:23], 0, v[0:1]
	s_mov_b32 m0, s42
	ds_read_b128 v[188:191], v165 offset:16384
	ds_read_b128 v[192:195], v165 offset:17408
	ds_read_b128 v[196:199], v165 offset:18432
	ds_read_b128 v[200:203], v165 offset:19456
	ds_read_b128 v[204:207], v165 offset:20480
	ds_read_b128 v[218:221], v165 offset:21504
	ds_read_b128 v[222:225], v165 offset:22528
	ds_read_b128 v[226:229], v165 offset:23552
	global_load_lds_dwordx4 v[160:161], off
	s_add_i32 m0, s42, 0x2000
	s_add_u32 s58, s22, 0x200000
	v_lshl_add_u64 v[178:179], s[22:23], 0, v[130:131]
	s_addc_u32 s59, s23, 0
	s_add_i32 s3, s3, s27
	global_load_lds_dwordx4 v[178:179], off
	v_lshl_add_u64 v[180:181], s[58:59], 0, v[0:1]
	s_mov_b32 m0, s3
	v_lshl_add_u64 v[182:183], s[24:25], 0, v[132:133]
	global_load_lds_dwordx4 v[180:181], off
	v_lshl_add_u64 v[180:181], s[58:59], 0, v[130:131]
	s_add_i32 m0, s3, 0x2000
	s_nop 0
	global_load_lds_dwordx4 v[180:181], off
	v_lshl_add_u64 v[180:181], s[24:25], 0, v[134:135]
	s_mov_b32 m0, s28
	s_nop 0
	global_load_lds_dwordx4 v[180:181], off
	s_mov_b32 m0, s29
	s_nop 0
	global_load_lds_dwordx4 v[182:183], off
	s_waitcnt vmcnt(8)
	s_waitcnt lgkmcnt(0)
	s_waitcnt lgkmcnt(0)
	v_mfma_f32_16x16x32_bf16 v[62:65], v[140:143], v[188:191], v[62:65]
	v_mfma_f32_16x16x32_bf16 v[58:61], v[148:151], v[188:191], v[58:61]
	v_mfma_f32_16x16x32_bf16 v[46:49], v[140:143], v[196:199], v[46:49]
	v_mfma_f32_16x16x32_bf16 v[42:45], v[148:151], v[196:199], v[42:45]
	s_barrier
	s_setprio 1
	v_mfma_f32_16x16x32_bf16 v[30:33], v[140:143], v[204:207], v[30:33]
	v_mfma_f32_16x16x32_bf16 v[26:29], v[148:151], v[204:207], v[26:29]
	v_mfma_f32_16x16x32_bf16 v[14:17], v[140:143], v[222:225], v[14:17]
	v_mfma_f32_16x16x32_bf16 v[10:13], v[148:151], v[222:225], v[10:13]
	v_mfma_f32_16x16x32_bf16 v[62:65], v[144:147], v[192:195], v[62:65]
	v_mfma_f32_16x16x32_bf16 v[58:61], v[152:155], v[192:195], v[58:61]
	v_mfma_f32_16x16x32_bf16 v[46:49], v[144:147], v[200:203], v[46:49]
	v_mfma_f32_16x16x32_bf16 v[42:45], v[152:155], v[200:203], v[42:45]
	v_mfma_f32_16x16x32_bf16 v[30:33], v[144:147], v[218:221], v[30:33]
	v_mfma_f32_16x16x32_bf16 v[26:29], v[152:155], v[218:221], v[26:29]
	v_mfma_f32_16x16x32_bf16 v[14:17], v[144:147], v[226:229], v[14:17]
	v_mfma_f32_16x16x32_bf16 v[10:13], v[152:155], v[226:229], v[10:13]
	s_setprio 0
	s_setprio 1
	v_mfma_f32_16x16x32_bf16 v[54:57], v[156:159], v[188:191], v[54:57]
	v_mfma_f32_16x16x32_bf16 v[50:53], v[170:173], v[188:191], v[50:53]
	v_mfma_f32_16x16x32_bf16 v[38:41], v[156:159], v[196:199], v[38:41]
	v_mfma_f32_16x16x32_bf16 v[34:37], v[170:173], v[196:199], v[34:37]
	v_mfma_f32_16x16x32_bf16 v[22:25], v[156:159], v[204:207], v[22:25]
	v_mfma_f32_16x16x32_bf16 v[18:21], v[170:173], v[204:207], v[18:21]
	v_mfma_f32_16x16x32_bf16 v[6:9], v[156:159], v[222:225], v[6:9]
	v_mfma_f32_16x16x32_bf16 v[2:5], v[170:173], v[222:225], v[2:5]
	v_mfma_f32_16x16x32_bf16 v[54:57], v[166:169], v[192:195], v[54:57]
	v_mfma_f32_16x16x32_bf16 v[50:53], v[174:177], v[192:195], v[50:53]
	v_mfma_f32_16x16x32_bf16 v[38:41], v[166:169], v[200:203], v[38:41]
	v_mfma_f32_16x16x32_bf16 v[34:37], v[174:177], v[200:203], v[34:37]
	v_mfma_f32_16x16x32_bf16 v[22:25], v[166:169], v[218:221], v[22:25]
	v_mfma_f32_16x16x32_bf16 v[18:21], v[174:177], v[218:221], v[18:21]
	v_mfma_f32_16x16x32_bf16 v[6:9], v[166:169], v[226:229], v[6:9]
	v_mfma_f32_16x16x32_bf16 v[2:5], v[174:177], v[226:229], v[2:5]
	s_setprio 0
	s_barrier
	s_add_i32 s3, 0, 0x18000
	s_add_i32 s42, 0, 0x1c000
	v_add_u32_e32 v152, s3, v163
	v_add_u32_e32 v174, s42, v163
	ds_read_b128 v[140:143], v152
	ds_read_b128 v[144:147], v152 offset:1024
	ds_read_b128 v[148:151], v152 offset:2048
	ds_read_b128 v[152:155], v152 offset:3072
	ds_read_b128 v[156:159], v174
	ds_read_b128 v[166:169], v174 offset:1024
	ds_read_b128 v[170:173], v174 offset:2048
	ds_read_b128 v[174:177], v174 offset:3072
	s_add_u32 s24, s24, 0x200000
	s_addc_u32 s25, s25, 0
	s_mov_b32 m0, s30
	v_lshl_add_u64 v[184:185], s[24:25], 0, v[134:135]
	ds_read_b128 v[188:191], v165 offset:32768
	ds_read_b128 v[192:195], v165 offset:33792
	ds_read_b128 v[196:199], v165 offset:34816
	ds_read_b128 v[200:203], v165 offset:35840
	ds_read_b128 v[204:207], v165 offset:36864
	ds_read_b128 v[218:221], v165 offset:37888
	ds_read_b128 v[222:225], v165 offset:38912
	ds_read_b128 v[226:229], v165 offset:39936
	global_load_lds_dwordx4 v[184:185], off
	v_lshl_add_u64 v[184:185], s[24:25], 0, v[132:133]
	s_mov_b32 m0, s31
	s_nop 0
	global_load_lds_dwordx4 v[184:185], off
	s_waitcnt vmcnt(8)
	s_waitcnt lgkmcnt(0)
	s_waitcnt lgkmcnt(0)
	v_mfma_f32_16x16x32_bf16 v[126:129], v[140:143], v[188:191], v[126:129]
	v_mfma_f32_16x16x32_bf16 v[122:125], v[148:151], v[188:191], v[122:125]
	v_mfma_f32_16x16x32_bf16 v[110:113], v[140:143], v[196:199], v[110:113]
	v_mfma_f32_16x16x32_bf16 v[106:109], v[148:151], v[196:199], v[106:109]
	s_barrier
	s_setprio 1
	v_mfma_f32_16x16x32_bf16 v[94:97], v[140:143], v[204:207], v[94:97]
	v_mfma_f32_16x16x32_bf16 v[90:93], v[148:151], v[204:207], v[90:93]
	v_mfma_f32_16x16x32_bf16 v[78:81], v[140:143], v[222:225], v[78:81]
	v_mfma_f32_16x16x32_bf16 v[74:77], v[148:151], v[222:225], v[74:77]
	v_mfma_f32_16x16x32_bf16 v[126:129], v[144:147], v[192:195], v[126:129]
	v_mfma_f32_16x16x32_bf16 v[122:125], v[152:155], v[192:195], v[122:125]
	v_mfma_f32_16x16x32_bf16 v[110:113], v[144:147], v[200:203], v[110:113]
	v_mfma_f32_16x16x32_bf16 v[106:109], v[152:155], v[200:203], v[106:109]
	v_mfma_f32_16x16x32_bf16 v[94:97], v[144:147], v[218:221], v[94:97]
	v_mfma_f32_16x16x32_bf16 v[90:93], v[152:155], v[218:221], v[90:93]
	v_mfma_f32_16x16x32_bf16 v[78:81], v[144:147], v[226:229], v[78:81]
	v_mfma_f32_16x16x32_bf16 v[74:77], v[152:155], v[226:229], v[74:77]
	s_setprio 0
	s_setprio 1
	v_mfma_f32_16x16x32_bf16 v[118:121], v[156:159], v[188:191], v[118:121]
	v_mfma_f32_16x16x32_bf16 v[114:117], v[170:173], v[188:191], v[114:117]
	v_mfma_f32_16x16x32_bf16 v[102:105], v[156:159], v[196:199], v[102:105]
	v_mfma_f32_16x16x32_bf16 v[98:101], v[170:173], v[196:199], v[98:101]
	v_mfma_f32_16x16x32_bf16 v[86:89], v[156:159], v[204:207], v[86:89]
	v_mfma_f32_16x16x32_bf16 v[82:85], v[170:173], v[204:207], v[82:85]
	v_mfma_f32_16x16x32_bf16 v[70:73], v[156:159], v[222:225], v[70:73]
	v_mfma_f32_16x16x32_bf16 v[66:69], v[170:173], v[222:225], v[66:69]
	v_mfma_f32_16x16x32_bf16 v[118:121], v[166:169], v[192:195], v[118:121]
	v_mfma_f32_16x16x32_bf16 v[114:117], v[174:177], v[192:195], v[114:117]
	v_mfma_f32_16x16x32_bf16 v[102:105], v[166:169], v[200:203], v[102:105]
	v_mfma_f32_16x16x32_bf16 v[98:101], v[174:177], v[200:203], v[98:101]
	v_mfma_f32_16x16x32_bf16 v[86:89], v[166:169], v[218:221], v[86:89]
	v_mfma_f32_16x16x32_bf16 v[82:85], v[174:177], v[218:221], v[82:85]
	v_mfma_f32_16x16x32_bf16 v[70:73], v[166:169], v[226:229], v[70:73]
	v_mfma_f32_16x16x32_bf16 v[66:69], v[174:177], v[226:229], v[66:69]
	s_setprio 0
	s_barrier
	s_add_i32 s3, s3, s27
	v_lshl_add_u64 v[160:161], v[160:161], 0, s[52:53]
	s_mov_b32 m0, s3
	ds_read_b128 v[188:191], v165 offset:49152
	ds_read_b128 v[192:195], v165 offset:50176
	ds_read_b128 v[196:199], v165 offset:51200
	ds_read_b128 v[200:203], v165 offset:52224
	ds_read_b128 v[204:207], v165 offset:53248
	ds_read_b128 v[218:221], v165 offset:54272
	ds_read_b128 v[222:225], v165 offset:55296
	ds_read_b128 v[226:229], v165 offset:56320
	global_load_lds_dwordx4 v[160:161], off
	s_add_i32 m0, s3, 0x2000
	s_add_u32 s22, s22, 0x200080
	v_lshl_add_u64 v[160:161], v[178:179], 0, s[52:53]
	s_addc_u32 s23, s23, 0
	s_add_i32 s3, s42, s27
	global_load_lds_dwordx4 v[160:161], off
	v_lshl_add_u64 v[160:161], s[22:23], 0, v[0:1]
	s_mov_b32 m0, s3
	s_nop 0
	global_load_lds_dwordx4 v[160:161], off
	v_lshl_add_u64 v[160:161], s[22:23], 0, v[130:131]
	s_add_i32 m0, s3, 0x2000
	s_nop 0
	global_load_lds_dwordx4 v[160:161], off
	v_lshl_add_u64 v[160:161], v[180:181], 0, s[52:53]
	s_mov_b32 m0, s34
	s_nop 0
	global_load_lds_dwordx4 v[160:161], off
	v_lshl_add_u64 v[160:161], v[182:183], 0, s[52:53]
	s_mov_b32 m0, s35
	s_nop 0
	global_load_lds_dwordx4 v[160:161], off
	s_waitcnt vmcnt(8)
	s_waitcnt lgkmcnt(0)
	s_waitcnt lgkmcnt(0)
	v_mfma_f32_16x16x32_bf16 v[62:65], v[140:143], v[188:191], v[62:65]
	v_mfma_f32_16x16x32_bf16 v[58:61], v[148:151], v[188:191], v[58:61]
	v_mfma_f32_16x16x32_bf16 v[46:49], v[140:143], v[196:199], v[46:49]
	v_mfma_f32_16x16x32_bf16 v[42:45], v[148:151], v[196:199], v[42:45]
	s_barrier
	s_setprio 1
	v_mfma_f32_16x16x32_bf16 v[30:33], v[140:143], v[204:207], v[30:33]
	v_mfma_f32_16x16x32_bf16 v[26:29], v[148:151], v[204:207], v[26:29]
	v_mfma_f32_16x16x32_bf16 v[14:17], v[140:143], v[222:225], v[14:17]
	v_mfma_f32_16x16x32_bf16 v[10:13], v[148:151], v[222:225], v[10:13]
	v_mfma_f32_16x16x32_bf16 v[62:65], v[144:147], v[192:195], v[62:65]
	v_mfma_f32_16x16x32_bf16 v[58:61], v[152:155], v[192:195], v[58:61]
	v_mfma_f32_16x16x32_bf16 v[46:49], v[144:147], v[200:203], v[46:49]
	v_mfma_f32_16x16x32_bf16 v[42:45], v[152:155], v[200:203], v[42:45]
	v_mfma_f32_16x16x32_bf16 v[30:33], v[144:147], v[218:221], v[30:33]
	v_mfma_f32_16x16x32_bf16 v[26:29], v[152:155], v[218:221], v[26:29]
	v_mfma_f32_16x16x32_bf16 v[14:17], v[144:147], v[226:229], v[14:17]
	v_mfma_f32_16x16x32_bf16 v[10:13], v[152:155], v[226:229], v[10:13]
	s_setprio 0
	s_setprio 1
	v_mfma_f32_16x16x32_bf16 v[54:57], v[156:159], v[188:191], v[54:57]
	v_mfma_f32_16x16x32_bf16 v[50:53], v[170:173], v[188:191], v[50:53]
	v_mfma_f32_16x16x32_bf16 v[38:41], v[156:159], v[196:199], v[38:41]
	v_mfma_f32_16x16x32_bf16 v[34:37], v[170:173], v[196:199], v[34:37]
	v_mfma_f32_16x16x32_bf16 v[22:25], v[156:159], v[204:207], v[22:25]
	v_mfma_f32_16x16x32_bf16 v[18:21], v[170:173], v[204:207], v[18:21]
	v_mfma_f32_16x16x32_bf16 v[6:9], v[156:159], v[222:225], v[6:9]
	v_mfma_f32_16x16x32_bf16 v[2:5], v[170:173], v[222:225], v[2:5]
	v_mfma_f32_16x16x32_bf16 v[54:57], v[166:169], v[192:195], v[54:57]
	v_mfma_f32_16x16x32_bf16 v[50:53], v[174:177], v[192:195], v[50:53]
	v_mfma_f32_16x16x32_bf16 v[38:41], v[166:169], v[200:203], v[38:41]
	v_mfma_f32_16x16x32_bf16 v[34:37], v[174:177], v[200:203], v[34:37]
	v_mfma_f32_16x16x32_bf16 v[22:25], v[166:169], v[218:221], v[22:25]
	v_mfma_f32_16x16x32_bf16 v[18:21], v[174:177], v[218:221], v[18:21]
	v_mfma_f32_16x16x32_bf16 v[6:9], v[166:169], v[226:229], v[6:9]
	v_mfma_f32_16x16x32_bf16 v[2:5], v[174:177], v[226:229], v[2:5]
	s_setprio 0
	s_barrier
	s_add_i32 s57, s57, 2
	s_add_u32 s20, s20, 0x100
	s_addc_u32 s21, s21, 0
	s_add_u32 s47, s47, 0x100
	s_addc_u32 s56, s56, 0
	s_cmpk_gt_u32 s57, 0x7d
	s_cbranch_scc0 .LBB0_1024
	s_and_b64 vcc, exec, s[10:11]
	s_mov_b32 s45, 0xa000
	s_cbranch_vccz .LBB0_1027
	s_barrier

.LBB0_1046:
	s_add_u32 s3, s18, 0xffe00080
	s_addc_u32 s20, s19, -1
	s_add_i32 s42, 0, 0x10000
	s_cmpk_eq_i32 s47, 0x7c
	s_cselect_b32 s23, s13, s20
	s_cselect_b32 s22, s41, s3
	s_cselect_b32 s21, s11, s46
	s_cselect_b32 s20, s44, s45
	s_add_i32 s3, 0, 0x14000
	v_add_u32_e32 v152, s42, v163
	v_add_u32_e32 v160, s3, v163
	ds_read_b128 v[140:143], v152
	ds_read_b128 v[144:147], v152 offset:1024
	ds_read_b128 v[148:151], v152 offset:2048
	ds_read_b128 v[152:155], v152 offset:3072
	ds_read_b128 v[156:159], v160
	ds_read_b128 v[166:169], v160 offset:1024
	ds_read_b128 v[170:173], v160 offset:2048
	ds_read_b128 v[174:177], v160 offset:3072
	v_lshl_add_u64 v[160:161], s[18:19], 0, v[136:137]
	s_add_i32 m0, s25, 0xc000
	ds_read_b128 v[188:191], v165
	ds_read_b128 v[192:195], v165 offset:1024
	ds_read_b128 v[196:199], v165 offset:2048
	ds_read_b128 v[200:203], v165 offset:3072
	ds_read_b128 v[204:207], v165 offset:4096
	ds_read_b128 v[218:221], v165 offset:5120
	ds_read_b128 v[222:225], v165 offset:6144
	ds_read_b128 v[226:229], v165 offset:7168
	global_load_lds_dwordx4 v[160:161], off
	v_lshl_add_u64 v[160:161], s[18:19], 0, v[138:139]
	s_add_i32 m0, s25, 0xe000
	s_nop 0
	global_load_lds_dwordx4 v[160:161], off
	s_waitcnt vmcnt(8)
	s_waitcnt lgkmcnt(0)
	s_waitcnt lgkmcnt(0)
	v_mfma_f32_16x16x32_bf16 v[126:129], v[140:143], v[188:191], v[126:129]
	v_mfma_f32_16x16x32_bf16 v[122:125], v[148:151], v[188:191], v[122:125]
	v_mfma_f32_16x16x32_bf16 v[110:113], v[140:143], v[196:199], v[110:113]
	v_mfma_f32_16x16x32_bf16 v[106:109], v[148:151], v[196:199], v[106:109]
	s_barrier
	s_setprio 1
	v_mfma_f32_16x16x32_bf16 v[94:97], v[140:143], v[204:207], v[94:97]
	v_mfma_f32_16x16x32_bf16 v[90:93], v[148:151], v[204:207], v[90:93]
	v_mfma_f32_16x16x32_bf16 v[78:81], v[140:143], v[222:225], v[78:81]
	v_mfma_f32_16x16x32_bf16 v[74:77], v[148:151], v[222:225], v[74:77]
	v_mfma_f32_16x16x32_bf16 v[126:129], v[144:147], v[192:195], v[126:129]
	v_mfma_f32_16x16x32_bf16 v[122:125], v[152:155], v[192:195], v[122:125]
	v_mfma_f32_16x16x32_bf16 v[110:113], v[144:147], v[200:203], v[110:113]
	v_mfma_f32_16x16x32_bf16 v[106:109], v[152:155], v[200:203], v[106:109]
	v_mfma_f32_16x16x32_bf16 v[94:97], v[144:147], v[218:221], v[94:97]
	v_mfma_f32_16x16x32_bf16 v[90:93], v[152:155], v[218:221], v[90:93]
	v_mfma_f32_16x16x32_bf16 v[78:81], v[144:147], v[226:229], v[78:81]
	v_mfma_f32_16x16x32_bf16 v[74:77], v[152:155], v[226:229], v[74:77]
	s_setprio 0
	s_setprio 1
	v_mfma_f32_16x16x32_bf16 v[118:121], v[156:159], v[188:191], v[118:121]
	v_mfma_f32_16x16x32_bf16 v[114:117], v[170:173], v[188:191], v[114:117]
	v_mfma_f32_16x16x32_bf16 v[102:105], v[156:159], v[196:199], v[102:105]
	v_mfma_f32_16x16x32_bf16 v[98:101], v[170:173], v[196:199], v[98:101]
	v_mfma_f32_16x16x32_bf16 v[86:89], v[156:159], v[204:207], v[86:89]
	v_mfma_f32_16x16x32_bf16 v[82:85], v[170:173], v[204:207], v[82:85]
	v_mfma_f32_16x16x32_bf16 v[70:73], v[156:159], v[222:225], v[70:73]
	v_mfma_f32_16x16x32_bf16 v[66:69], v[170:173], v[222:225], v[66:69]
	v_mfma_f32_16x16x32_bf16 v[118:121], v[166:169], v[192:195], v[118:121]
	v_mfma_f32_16x16x32_bf16 v[114:117], v[174:177], v[192:195], v[114:117]
	v_mfma_f32_16x16x32_bf16 v[102:105], v[166:169], v[200:203], v[102:105]
	v_mfma_f32_16x16x32_bf16 v[98:101], v[174:177], v[200:203], v[98:101]
	v_mfma_f32_16x16x32_bf16 v[86:89], v[166:169], v[218:221], v[86:89]
	v_mfma_f32_16x16x32_bf16 v[82:85], v[174:177], v[218:221], v[82:85]
	v_mfma_f32_16x16x32_bf16 v[70:73], v[166:169], v[226:229], v[70:73]
	v_mfma_f32_16x16x32_bf16 v[66:69], v[174:177], v[226:229], v[66:69]
	s_setprio 0
	s_barrier
	s_add_i32 s42, s42, s24
	v_lshl_add_u64 v[160:161], s[20:21], 0, v[0:1]
	s_mov_b32 m0, s42
	ds_read_b128 v[188:191], v165 offset:16384
	ds_read_b128 v[192:195], v165 offset:17408
	ds_read_b128 v[196:199], v165 offset:18432
	ds_read_b128 v[200:203], v165 offset:19456
	ds_read_b128 v[204:207], v165 offset:20480
	ds_read_b128 v[218:221], v165 offset:21504
	ds_read_b128 v[222:225], v165 offset:22528
	ds_read_b128 v[226:229], v165 offset:23552
	global_load_lds_dwordx4 v[160:161], off
	s_add_i32 m0, s42, 0x2000
	s_add_u32 s56, s20, 0x200000
	v_lshl_add_u64 v[178:179], s[20:21], 0, v[130:131]
	s_addc_u32 s57, s21, 0
	s_add_i32 s3, s3, s24
	global_load_lds_dwordx4 v[178:179], off
	v_lshl_add_u64 v[180:181], s[56:57], 0, v[0:1]
	s_mov_b32 m0, s3
	v_lshl_add_u64 v[182:183], s[22:23], 0, v[132:133]
	global_load_lds_dwordx4 v[180:181], off
	v_lshl_add_u64 v[180:181], s[56:57], 0, v[130:131]
	s_add_i32 m0, s3, 0x2000
	s_nop 0
	global_load_lds_dwordx4 v[180:181], off
	v_lshl_add_u64 v[180:181], s[22:23], 0, v[134:135]
	s_mov_b32 m0, s25
	s_nop 0
	global_load_lds_dwordx4 v[180:181], off
	s_mov_b32 m0, s27
	s_nop 0
	global_load_lds_dwordx4 v[182:183], off
	s_waitcnt vmcnt(8)
	s_waitcnt lgkmcnt(0)
	s_waitcnt lgkmcnt(0)
	v_mfma_f32_16x16x32_bf16 v[62:65], v[140:143], v[188:191], v[62:65]
	v_mfma_f32_16x16x32_bf16 v[58:61], v[148:151], v[188:191], v[58:61]
	v_mfma_f32_16x16x32_bf16 v[46:49], v[140:143], v[196:199], v[46:49]
	v_mfma_f32_16x16x32_bf16 v[42:45], v[148:151], v[196:199], v[42:45]
	s_barrier
	s_setprio 1
	v_mfma_f32_16x16x32_bf16 v[30:33], v[140:143], v[204:207], v[30:33]
	v_mfma_f32_16x16x32_bf16 v[26:29], v[148:151], v[204:207], v[26:29]
	v_mfma_f32_16x16x32_bf16 v[14:17], v[140:143], v[222:225], v[14:17]
	v_mfma_f32_16x16x32_bf16 v[10:13], v[148:151], v[222:225], v[10:13]
	v_mfma_f32_16x16x32_bf16 v[62:65], v[144:147], v[192:195], v[62:65]
	v_mfma_f32_16x16x32_bf16 v[58:61], v[152:155], v[192:195], v[58:61]
	v_mfma_f32_16x16x32_bf16 v[46:49], v[144:147], v[200:203], v[46:49]
	v_mfma_f32_16x16x32_bf16 v[42:45], v[152:155], v[200:203], v[42:45]
	v_mfma_f32_16x16x32_bf16 v[30:33], v[144:147], v[218:221], v[30:33]
	v_mfma_f32_16x16x32_bf16 v[26:29], v[152:155], v[218:221], v[26:29]
	v_mfma_f32_16x16x32_bf16 v[14:17], v[144:147], v[226:229], v[14:17]
	v_mfma_f32_16x16x32_bf16 v[10:13], v[152:155], v[226:229], v[10:13]
	s_setprio 0
	s_setprio 1
	v_mfma_f32_16x16x32_bf16 v[54:57], v[156:159], v[188:191], v[54:57]
	v_mfma_f32_16x16x32_bf16 v[50:53], v[170:173], v[188:191], v[50:53]
	v_mfma_f32_16x16x32_bf16 v[38:41], v[156:159], v[196:199], v[38:41]
	v_mfma_f32_16x16x32_bf16 v[34:37], v[170:173], v[196:199], v[34:37]
	v_mfma_f32_16x16x32_bf16 v[22:25], v[156:159], v[204:207], v[22:25]
	v_mfma_f32_16x16x32_bf16 v[18:21], v[170:173], v[204:207], v[18:21]
	v_mfma_f32_16x16x32_bf16 v[6:9], v[156:159], v[222:225], v[6:9]
	v_mfma_f32_16x16x32_bf16 v[2:5], v[170:173], v[222:225], v[2:5]
	v_mfma_f32_16x16x32_bf16 v[54:57], v[166:169], v[192:195], v[54:57]
	v_mfma_f32_16x16x32_bf16 v[50:53], v[174:177], v[192:195], v[50:53]
	v_mfma_f32_16x16x32_bf16 v[38:41], v[166:169], v[200:203], v[38:41]
	v_mfma_f32_16x16x32_bf16 v[34:37], v[174:177], v[200:203], v[34:37]
	v_mfma_f32_16x16x32_bf16 v[22:25], v[166:169], v[218:221], v[22:25]
	v_mfma_f32_16x16x32_bf16 v[18:21], v[174:177], v[218:221], v[18:21]
	v_mfma_f32_16x16x32_bf16 v[6:9], v[166:169], v[226:229], v[6:9]
	v_mfma_f32_16x16x32_bf16 v[2:5], v[174:177], v[226:229], v[2:5]
	s_setprio 0
	s_barrier
	s_add_i32 s3, 0, 0x18000
	s_add_i32 s42, 0, 0x1c000
	v_add_u32_e32 v152, s3, v163
	v_add_u32_e32 v174, s42, v163
	ds_read_b128 v[140:143], v152
	ds_read_b128 v[144:147], v152 offset:1024
	ds_read_b128 v[148:151], v152 offset:2048
	ds_read_b128 v[152:155], v152 offset:3072
	ds_read_b128 v[156:159], v174
	ds_read_b128 v[166:169], v174 offset:1024
	ds_read_b128 v[170:173], v174 offset:2048
	ds_read_b128 v[174:177], v174 offset:3072
	s_add_u32 s22, s22, 0x200000
	s_addc_u32 s23, s23, 0
	s_mov_b32 m0, s28
	v_lshl_add_u64 v[184:185], s[22:23], 0, v[134:135]
	ds_read_b128 v[188:191], v165 offset:32768
	ds_read_b128 v[192:195], v165 offset:33792
	ds_read_b128 v[196:199], v165 offset:34816
	ds_read_b128 v[200:203], v165 offset:35840
	ds_read_b128 v[204:207], v165 offset:36864
	ds_read_b128 v[218:221], v165 offset:37888
	ds_read_b128 v[222:225], v165 offset:38912
	ds_read_b128 v[226:229], v165 offset:39936
	global_load_lds_dwordx4 v[184:185], off
	v_lshl_add_u64 v[184:185], s[22:23], 0, v[132:133]
	s_mov_b32 m0, s29
	s_nop 0
	global_load_lds_dwordx4 v[184:185], off
	s_waitcnt vmcnt(8)
	s_waitcnt lgkmcnt(0)
	s_waitcnt lgkmcnt(0)
	v_mfma_f32_16x16x32_bf16 v[126:129], v[140:143], v[188:191], v[126:129]
	v_mfma_f32_16x16x32_bf16 v[122:125], v[148:151], v[188:191], v[122:125]
	v_mfma_f32_16x16x32_bf16 v[110:113], v[140:143], v[196:199], v[110:113]
	v_mfma_f32_16x16x32_bf16 v[106:109], v[148:151], v[196:199], v[106:109]
	s_barrier
	s_setprio 1
	v_mfma_f32_16x16x32_bf16 v[94:97], v[140:143], v[204:207], v[94:97]
	v_mfma_f32_16x16x32_bf16 v[90:93], v[148:151], v[204:207], v[90:93]
	v_mfma_f32_16x16x32_bf16 v[78:81], v[140:143], v[222:225], v[78:81]
	v_mfma_f32_16x16x32_bf16 v[74:77], v[148:151], v[222:225], v[74:77]
	v_mfma_f32_16x16x32_bf16 v[126:129], v[144:147], v[192:195], v[126:129]
	v_mfma_f32_16x16x32_bf16 v[122:125], v[152:155], v[192:195], v[122:125]
	v_mfma_f32_16x16x32_bf16 v[110:113], v[144:147], v[200:203], v[110:113]
	v_mfma_f32_16x16x32_bf16 v[106:109], v[152:155], v[200:203], v[106:109]
	v_mfma_f32_16x16x32_bf16 v[94:97], v[144:147], v[218:221], v[94:97]
	v_mfma_f32_16x16x32_bf16 v[90:93], v[152:155], v[218:221], v[90:93]
	v_mfma_f32_16x16x32_bf16 v[78:81], v[144:147], v[226:229], v[78:81]
	v_mfma_f32_16x16x32_bf16 v[74:77], v[152:155], v[226:229], v[74:77]
	s_setprio 0
	s_setprio 1
	v_mfma_f32_16x16x32_bf16 v[118:121], v[156:159], v[188:191], v[118:121]
	v_mfma_f32_16x16x32_bf16 v[114:117], v[170:173], v[188:191], v[114:117]
	v_mfma_f32_16x16x32_bf16 v[102:105], v[156:159], v[196:199], v[102:105]
	v_mfma_f32_16x16x32_bf16 v[98:101], v[170:173], v[196:199], v[98:101]
	v_mfma_f32_16x16x32_bf16 v[86:89], v[156:159], v[204:207], v[86:89]
	v_mfma_f32_16x16x32_bf16 v[82:85], v[170:173], v[204:207], v[82:85]
	v_mfma_f32_16x16x32_bf16 v[70:73], v[156:159], v[222:225], v[70:73]
	v_mfma_f32_16x16x32_bf16 v[66:69], v[170:173], v[222:225], v[66:69]
	v_mfma_f32_16x16x32_bf16 v[118:121], v[166:169], v[192:195], v[118:121]
	v_mfma_f32_16x16x32_bf16 v[114:117], v[174:177], v[192:195], v[114:117]
	v_mfma_f32_16x16x32_bf16 v[102:105], v[166:169], v[200:203], v[102:105]
	v_mfma_f32_16x16x32_bf16 v[98:101], v[174:177], v[200:203], v[98:101]
	v_mfma_f32_16x16x32_bf16 v[86:89], v[166:169], v[218:221], v[86:89]
	v_mfma_f32_16x16x32_bf16 v[82:85], v[174:177], v[218:221], v[82:85]
	v_mfma_f32_16x16x32_bf16 v[70:73], v[166:169], v[226:229], v[70:73]
	v_mfma_f32_16x16x32_bf16 v[66:69], v[174:177], v[226:229], v[66:69]
	s_setprio 0
	s_barrier
	s_add_i32 s3, s3, s24
	v_lshl_add_u64 v[160:161], v[160:161], 0, s[52:53]
	s_mov_b32 m0, s3
	ds_read_b128 v[188:191], v165 offset:49152
	ds_read_b128 v[192:195], v165 offset:50176
	ds_read_b128 v[196:199], v165 offset:51200
	ds_read_b128 v[200:203], v165 offset:52224
	ds_read_b128 v[204:207], v165 offset:53248
	ds_read_b128 v[218:221], v165 offset:54272
	ds_read_b128 v[222:225], v165 offset:55296
	ds_read_b128 v[226:229], v165 offset:56320
	global_load_lds_dwordx4 v[160:161], off
	s_add_i32 m0, s3, 0x2000
	s_add_u32 s20, s20, 0x200080
	v_lshl_add_u64 v[160:161], v[178:179], 0, s[52:53]
	s_addc_u32 s21, s21, 0
	s_add_i32 s3, s42, s24
	global_load_lds_dwordx4 v[160:161], off
	v_lshl_add_u64 v[160:161], s[20:21], 0, v[0:1]
	s_mov_b32 m0, s3
	s_nop 0
	global_load_lds_dwordx4 v[160:161], off
	v_lshl_add_u64 v[160:161], s[20:21], 0, v[130:131]
	s_add_i32 m0, s3, 0x2000
	s_nop 0
	global_load_lds_dwordx4 v[160:161], off
	v_lshl_add_u64 v[160:161], v[180:181], 0, s[52:53]
	s_mov_b32 m0, s30
	s_nop 0
	global_load_lds_dwordx4 v[160:161], off
	v_lshl_add_u64 v[160:161], v[182:183], 0, s[52:53]
	s_mov_b32 m0, s31
	s_nop 0
	global_load_lds_dwordx4 v[160:161], off
	s_waitcnt vmcnt(8)
	s_waitcnt lgkmcnt(0)
	s_waitcnt lgkmcnt(0)
	v_mfma_f32_16x16x32_bf16 v[62:65], v[140:143], v[188:191], v[62:65]
	v_mfma_f32_16x16x32_bf16 v[58:61], v[148:151], v[188:191], v[58:61]
	v_mfma_f32_16x16x32_bf16 v[46:49], v[140:143], v[196:199], v[46:49]
	v_mfma_f32_16x16x32_bf16 v[42:45], v[148:151], v[196:199], v[42:45]
	s_barrier
	s_setprio 1
	v_mfma_f32_16x16x32_bf16 v[30:33], v[140:143], v[204:207], v[30:33]
	v_mfma_f32_16x16x32_bf16 v[26:29], v[148:151], v[204:207], v[26:29]
	v_mfma_f32_16x16x32_bf16 v[14:17], v[140:143], v[222:225], v[14:17]
	v_mfma_f32_16x16x32_bf16 v[10:13], v[148:151], v[222:225], v[10:13]
	v_mfma_f32_16x16x32_bf16 v[62:65], v[144:147], v[192:195], v[62:65]
	v_mfma_f32_16x16x32_bf16 v[58:61], v[152:155], v[192:195], v[58:61]
	v_mfma_f32_16x16x32_bf16 v[46:49], v[144:147], v[200:203], v[46:49]
	v_mfma_f32_16x16x32_bf16 v[42:45], v[152:155], v[200:203], v[42:45]
	v_mfma_f32_16x16x32_bf16 v[30:33], v[144:147], v[218:221], v[30:33]
	v_mfma_f32_16x16x32_bf16 v[26:29], v[152:155], v[218:221], v[26:29]
	v_mfma_f32_16x16x32_bf16 v[14:17], v[144:147], v[226:229], v[14:17]
	v_mfma_f32_16x16x32_bf16 v[10:13], v[152:155], v[226:229], v[10:13]
	s_setprio 0
	s_setprio 1
	v_mfma_f32_16x16x32_bf16 v[54:57], v[156:159], v[188:191], v[54:57]
	v_mfma_f32_16x16x32_bf16 v[50:53], v[170:173], v[188:191], v[50:53]
	v_mfma_f32_16x16x32_bf16 v[38:41], v[156:159], v[196:199], v[38:41]
	v_mfma_f32_16x16x32_bf16 v[34:37], v[170:173], v[196:199], v[34:37]
	v_mfma_f32_16x16x32_bf16 v[22:25], v[156:159], v[204:207], v[22:25]
	v_mfma_f32_16x16x32_bf16 v[18:21], v[170:173], v[204:207], v[18:21]
	v_mfma_f32_16x16x32_bf16 v[6:9], v[156:159], v[222:225], v[6:9]
	v_mfma_f32_16x16x32_bf16 v[2:5], v[170:173], v[222:225], v[2:5]
	v_mfma_f32_16x16x32_bf16 v[54:57], v[166:169], v[192:195], v[54:57]
	v_mfma_f32_16x16x32_bf16 v[50:53], v[174:177], v[192:195], v[50:53]
	v_mfma_f32_16x16x32_bf16 v[38:41], v[166:169], v[200:203], v[38:41]
	v_mfma_f32_16x16x32_bf16 v[34:37], v[174:177], v[200:203], v[34:37]
	v_mfma_f32_16x16x32_bf16 v[22:25], v[166:169], v[218:221], v[22:25]
	v_mfma_f32_16x16x32_bf16 v[18:21], v[174:177], v[218:221], v[18:21]
	v_mfma_f32_16x16x32_bf16 v[6:9], v[166:169], v[226:229], v[6:9]
	v_mfma_f32_16x16x32_bf16 v[2:5], v[174:177], v[226:229], v[2:5]
	s_setprio 0
	s_barrier
	s_add_i32 s47, s47, 2
	s_add_u32 s18, s18, 0x100
	s_addc_u32 s19, s19, 0
	s_add_u32 s45, s45, 0x100
	s_addc_u32 s46, s46, 0
	s_cmpk_gt_u32 s47, 0x7d
	s_cbranch_scc0 .LBB0_1046
	s_and_b64 vcc, exec, s[8:9]
	s_movk_i32 s41, 0x6000
	s_mov_b32 s44, 0x8000
	s_mov_b32 s45, 0xa000
	s_cbranch_vccz .LBB0_1049
	s_barrier
